# v58 + closing setprio 0 behind the closing barrier + up accumulator clears replaced by C=0 first MFMAs
# speedup vs baseline: 1.0028x; 1.0028x over previous
; #define PG8_STAGE(bufoff, gbase, voff) do { _Pragma("unroll") for (int _i = 0; _i < 2; ++_i) \
;         __builtin_amdgcn_global_load_lds((const unsigned*)((const char*)(gbase) + (voff)[_i]), (LAS unsigned*)(lds + (bufoff) + ldsw + _i * 8192), 16, 0, 0); } while (0)
; #define PG8_LDA(dst, b, h) do { _Pragma("unroll") for (int m = 0; m < 4; ++m) _Pragma("unroll") for (int k = 0; k < 2; ++k) dst[m][k] = *(const LAS bf16x8*)(lds + PG8_SA(b, h) + aoff + m * 2048 + k * 1024); } while (0)
; #define PG8_LDB(dst, b, h) do { _Pragma("unroll") for (int n = 0; n < 2; ++n) _Pragma("unroll") for (int k = 0; k < 2; ++k) dst[n][k] = *(const LAS bf16x8*)(lds + PG8_SB(b, h) + boff + n * 2048 + k * 1024); } while (0)
; #define PG8_MMA(ai, bj, At, Bt) do { __builtin_amdgcn_s_setprio(1); _Pragma("unroll") for (int m = 0; m < 4; ++m) _Pragma("unroll") for (int n = 0; n < 2; ++n) _Pragma("unroll") for (int k = 0; k < 2; ++k) \
;         acc[ai][bj][m][n] = __builtin_amdgcn_mfma_f32_16x16x32_bf16(Bt[n][k], At[m][k], acc[ai][bj][m][n], 0, 0, 0); __builtin_amdgcn_s_setprio(0); } while (0)
; #define PG8_WAIT_V(n) asm volatile("s_waitcnt vmcnt(" #n ")" ::: "memory")
; #define PG8_WAIT_L(n) asm volatile("s_waitcnt lgkmcnt(" #n ")" ::: "memory")
; #define PG8_BAR __builtin_amdgcn_s_barrier()
; #define PG8_SCHED __builtin_amdgcn_sched_barrier(0)
; template <class Epi, int AMODE>
; __device__ __forceinline__ void gemm_phase(LAS unsigned char* lds, const Gemm g, const StaticOrder& S, const Epi& E, int stagger_us, int tid_in) {
;     ...
;             const bool last = (t == nt - 2);
;             const char* a1 = cA + (size_t)(t + 1) * kstep;
;             const char* a2 = last ? nA : cA + (size_t)(t + 2) * kstep; const char* b2 = last ? nB : cB + (size_t)(t + 2) * kstep;
;             const char* a3 = a2 + kstep; const char* b3 = b2 + kstep;
;             PG8_LDB(B0, 0, 0); PG8_LDB(B1, 0, 1); PG8_SCHED; PG8_LDA(At, 0, 0); PG8_STAGE(PG8_SA(1, 1), a1 + hstepA, voffA);
;             PG8_WAIT_V(8); PG8_WAIT_L(0); PG8_BAR; PG8_MMA(0, 0, At, B0); PG8_MMA(0, 1, At, B1); PG8_BAR; PG8_SCHED;
;             PG8_LDA(At, 0, 1); PG8_STAGE(PG8_SB(0, 0), b2, voffB); PG8_STAGE(PG8_SB(0, 1), b2 + hstepB, voffB); PG8_STAGE(PG8_SA(0, 0), a2, voffA);
.LBB0_396:
	s_add_u32 s4, s60, 0xfff80080
	s_addc_u32 s5, s61, -1
	s_add_i32 s30, 0, 0x10000
	s_cmp_eq_u32 s29, 28
	s_cselect_b32 s7, s27, s5
	s_cselect_b32 s6, s28, s4
	v_add_u32_e32 v140, s30, v162
	s_cselect_b32 s5, s49, vcc_hi
	s_cselect_b32 s4, s51, vcc_lo
	s_add_i32 s44, 0, 0x14000
	ds_read_b128 v[144:147], v140
	ds_read_b128 v[148:151], v140 offset:1024
	ds_read_b128 v[152:155], v140 offset:2048
	ds_read_b128 v[156:159], v140 offset:3072
	v_add_u32_e32 v140, s44, v162
	ds_read_b128 v[166:169], v140
	ds_read_b128 v[170:173], v140 offset:1024
	ds_read_b128 v[174:177], v140 offset:2048
	ds_read_b128 v[178:181], v140 offset:3072
	v_lshl_add_u64 v[140:141], s[60:61], 0, v[136:137]
	s_add_i32 m0, s57, 0xc000
	ds_read_b128 v[182:185], v164
	ds_read_b128 v[186:189], v164 offset:1024
	ds_read_b128 v[190:193], v164 offset:2048
	ds_read_b128 v[194:197], v164 offset:3072
	ds_read_b128 v[198:201], v164 offset:4096
	ds_read_b128 v[202:205], v164 offset:5120
	ds_read_b128 v[206:209], v164 offset:6144
	ds_read_b128 v[210:213], v164 offset:7168
	global_load_lds_dwordx4 v[140:141], off
	s_add_i32 m0, s57, 0xe000
	v_lshl_add_u64 v[140:141], s[60:61], 0, v[138:139]
	global_load_lds_dwordx4 v[140:141], off
	s_setprio 1
	s_waitcnt vmcnt(8) lgkmcnt(0)
	s_barrier
	v_mfma_f32_16x16x32_bf16 v[126:129], v[144:147], v[182:185], v[126:129]
	v_mfma_f32_16x16x32_bf16 v[122:125], v[152:155], v[182:185], v[122:125]
	v_mfma_f32_16x16x32_bf16 v[110:113], v[144:147], v[190:193], v[110:113]
	v_mfma_f32_16x16x32_bf16 v[106:109], v[152:155], v[190:193], v[106:109]
	v_mfma_f32_16x16x32_bf16 v[94:97], v[144:147], v[198:201], v[94:97]
	v_mfma_f32_16x16x32_bf16 v[90:93], v[152:155], v[198:201], v[90:93]
	v_mfma_f32_16x16x32_bf16 v[78:81], v[144:147], v[206:209], v[78:81]
	v_mfma_f32_16x16x32_bf16 v[74:77], v[152:155], v[206:209], v[74:77]
	v_mfma_f32_16x16x32_bf16 v[126:129], v[148:151], v[186:189], v[126:129]
	v_mfma_f32_16x16x32_bf16 v[122:125], v[156:159], v[186:189], v[122:125]
	v_mfma_f32_16x16x32_bf16 v[110:113], v[148:151], v[194:197], v[110:113]
	v_mfma_f32_16x16x32_bf16 v[106:109], v[156:159], v[194:197], v[106:109]
	v_mfma_f32_16x16x32_bf16 v[94:97], v[148:151], v[202:205], v[94:97]
	v_mfma_f32_16x16x32_bf16 v[90:93], v[156:159], v[202:205], v[90:93]
	v_mfma_f32_16x16x32_bf16 v[78:81], v[148:151], v[210:213], v[78:81]
	v_mfma_f32_16x16x32_bf16 v[74:77], v[156:159], v[210:213], v[74:77]
	v_mfma_f32_16x16x32_bf16 v[118:121], v[166:169], v[182:185], v[118:121]
	v_mfma_f32_16x16x32_bf16 v[114:117], v[174:177], v[182:185], v[114:117]
	v_mfma_f32_16x16x32_bf16 v[102:105], v[166:169], v[190:193], v[102:105]
	v_mfma_f32_16x16x32_bf16 v[98:101], v[174:177], v[190:193], v[98:101]
	v_mfma_f32_16x16x32_bf16 v[86:89], v[166:169], v[198:201], v[86:89]
	v_mfma_f32_16x16x32_bf16 v[82:85], v[174:177], v[198:201], v[82:85]
	v_mfma_f32_16x16x32_bf16 v[70:73], v[166:169], v[206:209], v[70:73]
	v_mfma_f32_16x16x32_bf16 v[66:69], v[174:177], v[206:209], v[66:69]
	v_mfma_f32_16x16x32_bf16 v[118:121], v[170:173], v[186:189], v[118:121]
	v_mfma_f32_16x16x32_bf16 v[114:117], v[178:181], v[186:189], v[114:117]
	v_mfma_f32_16x16x32_bf16 v[102:105], v[170:173], v[194:197], v[102:105]
	v_mfma_f32_16x16x32_bf16 v[98:101], v[178:181], v[194:197], v[98:101]
	v_mfma_f32_16x16x32_bf16 v[86:89], v[170:173], v[202:205], v[86:89]
	v_mfma_f32_16x16x32_bf16 v[82:85], v[178:181], v[202:205], v[82:85]
	v_mfma_f32_16x16x32_bf16 v[70:73], v[170:173], v[210:213], v[70:73]
	v_mfma_f32_16x16x32_bf16 v[66:69], v[178:181], v[210:213], v[66:69]
	s_barrier
	s_setprio 0
	s_add_i32 s30, s30, s66
	v_lshl_add_u64 v[140:141], s[4:5], 0, v[0:1]
	s_mov_b32 m0, s30
	ds_read_b128 v[182:185], v164 offset:16384
	ds_read_b128 v[186:189], v164 offset:17408
	ds_read_b128 v[190:193], v164 offset:18432
	ds_read_b128 v[194:197], v164 offset:19456
	ds_read_b128 v[198:201], v164 offset:20480
	ds_read_b128 v[202:205], v164 offset:21504
	ds_read_b128 v[206:209], v164 offset:22528
	ds_read_b128 v[210:213], v164 offset:23552
	global_load_lds_dwordx4 v[140:141], off
	s_add_i32 m0, s30, 0x2000
	s_add_u32 s30, s4, 0x80000
	v_lshl_add_u64 v[160:161], s[4:5], 0, v[130:131]
	s_addc_u32 s31, s5, 0
	s_add_i32 s44, s44, s66
	global_load_lds_dwordx4 v[160:161], off
	v_lshl_add_u64 v[214:215], s[30:31], 0, v[0:1]
	s_mov_b32 m0, s44
	v_lshl_add_u64 v[216:217], s[6:7], 0, v[132:133]
	global_load_lds_dwordx4 v[214:215], off
	s_add_i32 m0, s44, 0x2000
	v_lshl_add_u64 v[214:215], s[30:31], 0, v[130:131]
	global_load_lds_dwordx4 v[214:215], off
	s_mov_b32 m0, s57
	v_lshl_add_u64 v[214:215], s[6:7], 0, v[134:135]
	global_load_lds_dwordx4 v[214:215], off
	s_mov_b32 m0, s59
	s_nop 0
	global_load_lds_dwordx4 v[216:217], off
	s_setprio 1
	s_waitcnt vmcnt(8) lgkmcnt(0)
	s_barrier
; #define PG8_STAGE(bufoff, gbase, voff) do { _Pragma("unroll") for (int _i = 0; _i < 2; ++_i) \
;         __builtin_amdgcn_global_load_lds((const unsigned*)((const char*)(gbase) + (voff)[_i]), (LAS unsigned*)(lds + (bufoff) + ldsw + _i * 8192), 16, 0, 0); } while (0)
; #define PG8_LDA(dst, b, h) do { _Pragma("unroll") for (int m = 0; m < 4; ++m) _Pragma("unroll") for (int k = 0; k < 2; ++k) dst[m][k] = *(const LAS bf16x8*)(lds + PG8_SA(b, h) + aoff + m * 2048 + k * 1024); } while (0)
; #define PG8_LDB(dst, b, h) do { _Pragma("unroll") for (int n = 0; n < 2; ++n) _Pragma("unroll") for (int k = 0; k < 2; ++k) dst[n][k] = *(const LAS bf16x8*)(lds + PG8_SB(b, h) + boff + n * 2048 + k * 1024); } while (0)
; #define PG8_MMA(ai, bj, At, Bt) do { __builtin_amdgcn_s_setprio(1); _Pragma("unroll") for (int m = 0; m < 4; ++m) _Pragma("unroll") for (int n = 0; n < 2; ++n) _Pragma("unroll") for (int k = 0; k < 2; ++k) \
;         acc[ai][bj][m][n] = __builtin_amdgcn_mfma_f32_16x16x32_bf16(Bt[n][k], At[m][k], acc[ai][bj][m][n], 0, 0, 0); __builtin_amdgcn_s_setprio(0); } while (0)
; #define PG8_WAIT_V(n) asm volatile("s_waitcnt vmcnt(" #n ")" ::: "memory")
; #define PG8_WAIT_L(n) asm volatile("s_waitcnt lgkmcnt(" #n ")" ::: "memory")
; #define PG8_BAR __builtin_amdgcn_s_barrier()
; #define PG8_SCHED __builtin_amdgcn_sched_barrier(0)
; template <class Epi, int AMODE>
; __device__ __forceinline__ void gemm_phase(LAS unsigned char* lds, const Gemm g, const StaticOrder& S, const Epi& E, int stagger_us, int tid_in) {
;     ...
;             PG8_WAIT_V(8); PG8_WAIT_L(0); PG8_BAR; PG8_MMA(1, 0, At, B0); PG8_MMA(1, 1, At, B1); PG8_BAR; PG8_SCHED;
;             PG8_LDB(B0, 1, 0); PG8_LDB(B1, 1, 1); PG8_SCHED; PG8_LDA(At, 1, 0); PG8_STAGE(PG8_SA(0, 1), a2 + hstepA, voffA);
;             PG8_WAIT_V(8); PG8_WAIT_L(0); PG8_BAR; PG8_MMA(0, 0, At, B0); PG8_MMA(0, 1, At, B1); PG8_BAR; PG8_SCHED;
	v_mfma_f32_16x16x32_bf16 v[62:65], v[144:147], v[182:185], v[62:65]
	v_mfma_f32_16x16x32_bf16 v[58:61], v[152:155], v[182:185], v[58:61]
	v_mfma_f32_16x16x32_bf16 v[46:49], v[144:147], v[190:193], v[46:49]
	v_mfma_f32_16x16x32_bf16 v[42:45], v[152:155], v[190:193], v[42:45]
	v_mfma_f32_16x16x32_bf16 v[30:33], v[144:147], v[198:201], v[30:33]
	v_mfma_f32_16x16x32_bf16 v[26:29], v[152:155], v[198:201], v[26:29]
	v_mfma_f32_16x16x32_bf16 v[14:17], v[144:147], v[206:209], v[14:17]
	v_mfma_f32_16x16x32_bf16 v[10:13], v[152:155], v[206:209], v[10:13]
	v_mfma_f32_16x16x32_bf16 v[62:65], v[148:151], v[186:189], v[62:65]
	v_mfma_f32_16x16x32_bf16 v[58:61], v[156:159], v[186:189], v[58:61]
	v_mfma_f32_16x16x32_bf16 v[46:49], v[148:151], v[194:197], v[46:49]
	v_mfma_f32_16x16x32_bf16 v[42:45], v[156:159], v[194:197], v[42:45]
	v_mfma_f32_16x16x32_bf16 v[30:33], v[148:151], v[202:205], v[30:33]
	v_mfma_f32_16x16x32_bf16 v[26:29], v[156:159], v[202:205], v[26:29]
	v_mfma_f32_16x16x32_bf16 v[14:17], v[148:151], v[210:213], v[14:17]
	v_mfma_f32_16x16x32_bf16 v[10:13], v[156:159], v[210:213], v[10:13]
	v_mfma_f32_16x16x32_bf16 v[54:57], v[166:169], v[182:185], v[54:57]
	v_mfma_f32_16x16x32_bf16 v[50:53], v[174:177], v[182:185], v[50:53]
	v_mfma_f32_16x16x32_bf16 v[38:41], v[166:169], v[190:193], v[38:41]
	v_mfma_f32_16x16x32_bf16 v[34:37], v[174:177], v[190:193], v[34:37]
	v_mfma_f32_16x16x32_bf16 v[22:25], v[166:169], v[198:201], v[22:25]
	v_mfma_f32_16x16x32_bf16 v[18:21], v[174:177], v[198:201], v[18:21]
	v_mfma_f32_16x16x32_bf16 v[6:9], v[166:169], v[206:209], v[6:9]
	v_mfma_f32_16x16x32_bf16 v[2:5], v[174:177], v[206:209], v[2:5]
	v_mfma_f32_16x16x32_bf16 v[54:57], v[170:173], v[186:189], v[54:57]
	v_mfma_f32_16x16x32_bf16 v[50:53], v[178:181], v[186:189], v[50:53]
	v_mfma_f32_16x16x32_bf16 v[38:41], v[170:173], v[194:197], v[38:41]
	v_mfma_f32_16x16x32_bf16 v[34:37], v[178:181], v[194:197], v[34:37]
	v_mfma_f32_16x16x32_bf16 v[22:25], v[170:173], v[202:205], v[22:25]
	v_mfma_f32_16x16x32_bf16 v[18:21], v[178:181], v[202:205], v[18:21]
	v_mfma_f32_16x16x32_bf16 v[6:9], v[170:173], v[210:213], v[6:9]
	v_mfma_f32_16x16x32_bf16 v[2:5], v[178:181], v[210:213], v[2:5]
	s_barrier
	s_setprio 0
	s_add_i32 s30, 0, 0x18000
	v_add_u32_e32 v142, s30, v162
	s_add_i32 s31, 0, 0x1c000
	ds_read_b128 v[144:147], v142
	ds_read_b128 v[148:151], v142 offset:1024
	ds_read_b128 v[152:155], v142 offset:2048
	ds_read_b128 v[156:159], v142 offset:3072
	v_add_u32_e32 v142, s31, v162
	ds_read_b128 v[166:169], v142
	ds_read_b128 v[170:173], v142 offset:1024
	ds_read_b128 v[174:177], v142 offset:2048
	ds_read_b128 v[178:181], v142 offset:3072
	s_add_u32 s6, s6, 0x80000
	s_addc_u32 s7, s7, 0
	s_mov_b32 m0, s87
	v_lshl_add_u64 v[218:219], s[6:7], 0, v[134:135]
	ds_read_b128 v[182:185], v164 offset:32768
	ds_read_b128 v[186:189], v164 offset:33792
	ds_read_b128 v[190:193], v164 offset:34816
	ds_read_b128 v[194:197], v164 offset:35840
	ds_read_b128 v[198:201], v164 offset:36864
	ds_read_b128 v[202:205], v164 offset:37888
	ds_read_b128 v[206:209], v164 offset:38912
	ds_read_b128 v[210:213], v164 offset:39936
	global_load_lds_dwordx4 v[218:219], off
	s_mov_b32 m0, s91
	v_lshl_add_u64 v[218:219], s[6:7], 0, v[132:133]
	global_load_lds_dwordx4 v[218:219], off
	s_setprio 1
	s_waitcnt vmcnt(8) lgkmcnt(0)
	s_barrier
	v_mfma_f32_16x16x32_bf16 v[126:129], v[144:147], v[182:185], v[126:129]
	v_mfma_f32_16x16x32_bf16 v[122:125], v[152:155], v[182:185], v[122:125]
	v_mfma_f32_16x16x32_bf16 v[110:113], v[144:147], v[190:193], v[110:113]
	v_mfma_f32_16x16x32_bf16 v[106:109], v[152:155], v[190:193], v[106:109]
	v_mfma_f32_16x16x32_bf16 v[94:97], v[144:147], v[198:201], v[94:97]
	v_mfma_f32_16x16x32_bf16 v[90:93], v[152:155], v[198:201], v[90:93]
	v_mfma_f32_16x16x32_bf16 v[78:81], v[144:147], v[206:209], v[78:81]
	v_mfma_f32_16x16x32_bf16 v[74:77], v[152:155], v[206:209], v[74:77]
	v_mfma_f32_16x16x32_bf16 v[126:129], v[148:151], v[186:189], v[126:129]
	v_mfma_f32_16x16x32_bf16 v[122:125], v[156:159], v[186:189], v[122:125]
	v_mfma_f32_16x16x32_bf16 v[110:113], v[148:151], v[194:197], v[110:113]
	v_mfma_f32_16x16x32_bf16 v[106:109], v[156:159], v[194:197], v[106:109]
	v_mfma_f32_16x16x32_bf16 v[94:97], v[148:151], v[202:205], v[94:97]
	v_mfma_f32_16x16x32_bf16 v[90:93], v[156:159], v[202:205], v[90:93]
	v_mfma_f32_16x16x32_bf16 v[78:81], v[148:151], v[210:213], v[78:81]
	v_mfma_f32_16x16x32_bf16 v[74:77], v[156:159], v[210:213], v[74:77]
	v_mfma_f32_16x16x32_bf16 v[118:121], v[166:169], v[182:185], v[118:121]
	v_mfma_f32_16x16x32_bf16 v[114:117], v[174:177], v[182:185], v[114:117]
	v_mfma_f32_16x16x32_bf16 v[102:105], v[166:169], v[190:193], v[102:105]
	v_mfma_f32_16x16x32_bf16 v[98:101], v[174:177], v[190:193], v[98:101]
	v_mfma_f32_16x16x32_bf16 v[86:89], v[166:169], v[198:201], v[86:89]
	v_mfma_f32_16x16x32_bf16 v[82:85], v[174:177], v[198:201], v[82:85]
	v_mfma_f32_16x16x32_bf16 v[70:73], v[166:169], v[206:209], v[70:73]
	v_mfma_f32_16x16x32_bf16 v[66:69], v[174:177], v[206:209], v[66:69]
	v_mfma_f32_16x16x32_bf16 v[118:121], v[170:173], v[186:189], v[118:121]
	v_mfma_f32_16x16x32_bf16 v[114:117], v[178:181], v[186:189], v[114:117]
	v_mfma_f32_16x16x32_bf16 v[102:105], v[170:173], v[194:197], v[102:105]
	v_mfma_f32_16x16x32_bf16 v[98:101], v[178:181], v[194:197], v[98:101]
	v_mfma_f32_16x16x32_bf16 v[86:89], v[170:173], v[202:205], v[86:89]
	v_mfma_f32_16x16x32_bf16 v[82:85], v[178:181], v[202:205], v[82:85]
	v_mfma_f32_16x16x32_bf16 v[70:73], v[170:173], v[210:213], v[70:73]
	v_mfma_f32_16x16x32_bf16 v[66:69], v[178:181], v[210:213], v[66:69]
	s_barrier
; #define PG8_STAGE(bufoff, gbase, voff) do { _Pragma("unroll") for (int _i = 0; _i < 2; ++_i) \
;         __builtin_amdgcn_global_load_lds((const unsigned*)((const char*)(gbase) + (voff)[_i]), (LAS unsigned*)(lds + (bufoff) + ldsw + _i * 8192), 16, 0, 0); } while (0)
; #define PG8_LDA(dst, b, h) do { _Pragma("unroll") for (int m = 0; m < 4; ++m) _Pragma("unroll") for (int k = 0; k < 2; ++k) dst[m][k] = *(const LAS bf16x8*)(lds + PG8_SA(b, h) + aoff + m * 2048 + k * 1024); } while (0)
; #define PG8_MMA(ai, bj, At, Bt) do { __builtin_amdgcn_s_setprio(1); _Pragma("unroll") for (int m = 0; m < 4; ++m) _Pragma("unroll") for (int n = 0; n < 2; ++n) _Pragma("unroll") for (int k = 0; k < 2; ++k) \
;         acc[ai][bj][m][n] = __builtin_amdgcn_mfma_f32_16x16x32_bf16(Bt[n][k], At[m][k], acc[ai][bj][m][n], 0, 0, 0); __builtin_amdgcn_s_setprio(0); } while (0)
; #define PG8_WAIT_V(n) asm volatile("s_waitcnt vmcnt(" #n ")" ::: "memory")
; #define PG8_WAIT_L(n) asm volatile("s_waitcnt lgkmcnt(" #n ")" ::: "memory")
; #define PG8_BAR __builtin_amdgcn_s_barrier()
; #define PG8_SCHED __builtin_amdgcn_sched_barrier(0)
; template <class Epi, int AMODE>
; __device__ __forceinline__ void gemm_phase(LAS unsigned char* lds, const Gemm g, const StaticOrder& S, const Epi& E, int stagger_us, int tid_in) {
;     ...
;             PG8_LDA(At, 1, 1); PG8_STAGE(PG8_SB(1, 0), b3, voffB); PG8_STAGE(PG8_SB(1, 1), b3 + hstepB, voffB); PG8_STAGE(PG8_SA(1, 0), a3, voffA);
;             PG8_WAIT_V(8); PG8_WAIT_L(0); PG8_BAR; PG8_MMA(1, 0, At, B0); PG8_MMA(1, 1, At, B1); PG8_BAR; PG8_SCHED;
;         }
;         if (wr == 0) PG8_BAR;
	s_setprio 0
	s_add_i32 s6, s30, s66
	v_lshl_add_u64 v[140:141], v[140:141], 0, s[74:75]
	s_mov_b32 m0, s6
	ds_read_b128 v[182:185], v164 offset:49152
	ds_read_b128 v[186:189], v164 offset:50176
	ds_read_b128 v[190:193], v164 offset:51200
	ds_read_b128 v[194:197], v164 offset:52224
	ds_read_b128 v[198:201], v164 offset:53248
	ds_read_b128 v[202:205], v164 offset:54272
	ds_read_b128 v[206:209], v164 offset:55296
	ds_read_b128 v[210:213], v164 offset:56320
	global_load_lds_dwordx4 v[140:141], off
	s_add_i32 m0, s6, 0x2000
	s_add_u32 s4, s4, 0x80080
	v_lshl_add_u64 v[140:141], v[160:161], 0, s[74:75]
	s_addc_u32 s5, s5, 0
	s_add_i32 s6, s31, s66
	global_load_lds_dwordx4 v[140:141], off
	s_mov_b32 m0, s6
	v_lshl_add_u64 v[140:141], s[4:5], 0, v[0:1]
	global_load_lds_dwordx4 v[140:141], off
	s_add_i32 m0, s6, 0x2000
	v_lshl_add_u64 v[140:141], s[4:5], 0, v[130:131]
	global_load_lds_dwordx4 v[140:141], off
	s_mov_b32 m0, s95
	v_lshl_add_u64 v[140:141], v[214:215], 0, s[74:75]
	global_load_lds_dwordx4 v[140:141], off
	s_mov_b32 m0, s96
	v_lshl_add_u64 v[140:141], v[216:217], 0, s[74:75]
	global_load_lds_dwordx4 v[140:141], off
	s_setprio 1
	s_waitcnt vmcnt(8) lgkmcnt(0)
	s_barrier
	v_mfma_f32_16x16x32_bf16 v[62:65], v[144:147], v[182:185], v[62:65]
	v_mfma_f32_16x16x32_bf16 v[58:61], v[152:155], v[182:185], v[58:61]
	v_mfma_f32_16x16x32_bf16 v[46:49], v[144:147], v[190:193], v[46:49]
	v_mfma_f32_16x16x32_bf16 v[42:45], v[152:155], v[190:193], v[42:45]
	v_mfma_f32_16x16x32_bf16 v[30:33], v[144:147], v[198:201], v[30:33]
	v_mfma_f32_16x16x32_bf16 v[26:29], v[152:155], v[198:201], v[26:29]
	v_mfma_f32_16x16x32_bf16 v[14:17], v[144:147], v[206:209], v[14:17]
	v_mfma_f32_16x16x32_bf16 v[10:13], v[152:155], v[206:209], v[10:13]
	v_mfma_f32_16x16x32_bf16 v[62:65], v[148:151], v[186:189], v[62:65]
	v_mfma_f32_16x16x32_bf16 v[58:61], v[156:159], v[186:189], v[58:61]
	v_mfma_f32_16x16x32_bf16 v[46:49], v[148:151], v[194:197], v[46:49]
	v_mfma_f32_16x16x32_bf16 v[42:45], v[156:159], v[194:197], v[42:45]
	v_mfma_f32_16x16x32_bf16 v[30:33], v[148:151], v[202:205], v[30:33]
	v_mfma_f32_16x16x32_bf16 v[26:29], v[156:159], v[202:205], v[26:29]
	v_mfma_f32_16x16x32_bf16 v[14:17], v[148:151], v[210:213], v[14:17]
	v_mfma_f32_16x16x32_bf16 v[10:13], v[156:159], v[210:213], v[10:13]
	v_mfma_f32_16x16x32_bf16 v[54:57], v[166:169], v[182:185], v[54:57]
	v_mfma_f32_16x16x32_bf16 v[50:53], v[174:177], v[182:185], v[50:53]
	v_mfma_f32_16x16x32_bf16 v[38:41], v[166:169], v[190:193], v[38:41]
	v_mfma_f32_16x16x32_bf16 v[34:37], v[174:177], v[190:193], v[34:37]
	v_mfma_f32_16x16x32_bf16 v[22:25], v[166:169], v[198:201], v[22:25]
	v_mfma_f32_16x16x32_bf16 v[18:21], v[174:177], v[198:201], v[18:21]
	v_mfma_f32_16x16x32_bf16 v[6:9], v[166:169], v[206:209], v[6:9]
	v_mfma_f32_16x16x32_bf16 v[2:5], v[174:177], v[206:209], v[2:5]
	v_mfma_f32_16x16x32_bf16 v[54:57], v[170:173], v[186:189], v[54:57]
	v_mfma_f32_16x16x32_bf16 v[50:53], v[178:181], v[186:189], v[50:53]
	v_mfma_f32_16x16x32_bf16 v[38:41], v[170:173], v[194:197], v[38:41]
	v_mfma_f32_16x16x32_bf16 v[34:37], v[178:181], v[194:197], v[34:37]
	v_mfma_f32_16x16x32_bf16 v[22:25], v[170:173], v[202:205], v[22:25]
	v_mfma_f32_16x16x32_bf16 v[18:21], v[178:181], v[202:205], v[18:21]
	v_mfma_f32_16x16x32_bf16 v[6:9], v[170:173], v[210:213], v[6:9]
	v_mfma_f32_16x16x32_bf16 v[2:5], v[178:181], v[210:213], v[2:5]
	s_barrier
	s_setprio 0
	s_add_i32 s29, s29, 2
	s_add_u32 s60, s60, 0x100
	s_addc_u32 s61, s61, 0
	s_add_u32 vcc_lo, vcc_lo, 0x100
	s_addc_u32 vcc_hi, vcc_hi, 0
	s_cmp_gt_u32 s29, 29
	s_cbranch_scc0 .LBB0_396
	s_and_b64 vcc, exec, s[46:47]
	s_cbranch_vccz .LBB0_399
	s_barrier

; #define PG8_STAGE(bufoff, gbase, voff) do { _Pragma("unroll") for (int _i = 0; _i < 2; ++_i) \
;         __builtin_amdgcn_global_load_lds((const unsigned*)((const char*)(gbase) + (voff)[_i]), (LAS unsigned*)(lds + (bufoff) + ldsw + _i * 8192), 16, 0, 0); } while (0)
; #define PG8_LDA(dst, b, h) do { _Pragma("unroll") for (int m = 0; m < 4; ++m) _Pragma("unroll") for (int k = 0; k < 2; ++k) dst[m][k] = *(const LAS bf16x8*)(lds + PG8_SA(b, h) + aoff + m * 2048 + k * 1024); } while (0)
; #define PG8_LDB(dst, b, h) do { _Pragma("unroll") for (int n = 0; n < 2; ++n) _Pragma("unroll") for (int k = 0; k < 2; ++k) dst[n][k] = *(const LAS bf16x8*)(lds + PG8_SB(b, h) + boff + n * 2048 + k * 1024); } while (0)
; #define PG8_MMA(ai, bj, At, Bt) do { __builtin_amdgcn_s_setprio(1); _Pragma("unroll") for (int m = 0; m < 4; ++m) _Pragma("unroll") for (int n = 0; n < 2; ++n) _Pragma("unroll") for (int k = 0; k < 2; ++k) \
;         acc[ai][bj][m][n] = __builtin_amdgcn_mfma_f32_16x16x32_bf16(Bt[n][k], At[m][k], acc[ai][bj][m][n], 0, 0, 0); __builtin_amdgcn_s_setprio(0); } while (0)
; #define PG8_WAIT_V(n) asm volatile("s_waitcnt vmcnt(" #n ")" ::: "memory")
; #define PG8_WAIT_L(n) asm volatile("s_waitcnt lgkmcnt(" #n ")" ::: "memory")
; #define PG8_BAR __builtin_amdgcn_s_barrier()
; #define PG8_SCHED __builtin_amdgcn_sched_barrier(0)
; template <class Epi, int AMODE>
; __device__ __forceinline__ void gemm_phase(LAS unsigned char* lds, const Gemm g, const StaticOrder& S, const Epi& E, int stagger_us, int tid_in) {
;     ...
;             const bool last = (t == nt - 2);
;             const char* a1 = cA + (size_t)(t + 1) * kstep;
;             const char* a2 = last ? nA : cA + (size_t)(t + 2) * kstep; const char* b2 = last ? nB : cB + (size_t)(t + 2) * kstep;
;             const char* a3 = a2 + kstep; const char* b3 = b2 + kstep;
;             PG8_LDB(B0, 0, 0); PG8_LDB(B1, 0, 1); PG8_SCHED; PG8_LDA(At, 0, 0); PG8_STAGE(PG8_SA(1, 1), a1 + hstepA, voffA);
;             PG8_WAIT_V(8); PG8_WAIT_L(0); PG8_BAR; PG8_MMA(0, 0, At, B0); PG8_MMA(0, 1, At, B1); PG8_BAR; PG8_SCHED;
;             PG8_LDA(At, 0, 1); PG8_STAGE(PG8_SB(0, 0), b2, voffB); PG8_STAGE(PG8_SB(0, 1), b2 + hstepB, voffB); PG8_STAGE(PG8_SA(0, 0), a2, voffA);
.LBB0_1199:
	s_add_u32 s4, s46, 0x100
	s_addc_u32 s5, s47, 0
	s_add_i32 s34, 0, 0x10000
	s_cmp_eq_u32 s31, 28
	s_cselect_b32 s95, s61, s5
	s_cselect_b32 s94, vcc_lo, s4
	s_cselect_b32 s7, s59, s30
	s_cselect_b32 s6, vcc_hi, s29
	s_add_i32 s35, 0, 0x14000
	v_add_u32_e32 v62, s34, v205
	v_add_u32_e32 v158, s35, v205
	ds_read_b128 v[50:53], v62
	ds_read_b128 v[54:57], v62 offset:1024
	ds_read_b128 v[58:61], v62 offset:2048
	ds_read_b128 v[62:65], v62 offset:3072
	ds_read_b128 v[146:149], v158
	ds_read_b128 v[150:153], v158 offset:1024
	ds_read_b128 v[154:157], v158 offset:2048
	ds_read_b128 v[158:161], v158 offset:3072
	v_lshl_add_u64 v[200:201], s[46:47], 0, v[176:177]
	s_add_i32 m0, s66, 0xc000
	ds_read_b128 v[162:165], v207
	ds_read_b128 v[166:169], v207 offset:1024
	ds_read_b128 v[170:173], v207 offset:2048
	ds_read_b128 v[180:183], v207 offset:3072
	ds_read_b128 v[184:187], v207 offset:4096
	ds_read_b128 v[188:191], v207 offset:5120
	ds_read_b128 v[192:195], v207 offset:6144
	ds_read_b128 v[196:199], v207 offset:7168
	global_load_lds_dwordx4 v[200:201], off
	s_add_i32 m0, s66, 0xe000
	v_lshl_add_u64 v[200:201], s[46:47], 0, v[178:179]
	global_load_lds_dwordx4 v[200:201], off
	s_setprio 1
	s_waitcnt vmcnt(8) lgkmcnt(0)
	s_barrier
	v_mfma_f32_16x16x32_bf16 v[142:145], v[50:53], v[162:165], v[142:145]
	v_mfma_f32_16x16x32_bf16 v[138:141], v[58:61], v[162:165], v[138:141]
	v_mfma_f32_16x16x32_bf16 v[126:129], v[50:53], v[170:173], v[126:129]
	v_mfma_f32_16x16x32_bf16 v[122:125], v[58:61], v[170:173], v[122:125]
	v_mfma_f32_16x16x32_bf16 v[110:113], v[50:53], v[184:187], v[110:113]
	v_mfma_f32_16x16x32_bf16 v[106:109], v[58:61], v[184:187], v[106:109]
	v_mfma_f32_16x16x32_bf16 v[94:97], v[50:53], v[192:195], v[94:97]
	v_mfma_f32_16x16x32_bf16 v[90:93], v[58:61], v[192:195], v[90:93]
	v_mfma_f32_16x16x32_bf16 v[142:145], v[54:57], v[166:169], v[142:145]
	v_mfma_f32_16x16x32_bf16 v[138:141], v[62:65], v[166:169], v[138:141]
	v_mfma_f32_16x16x32_bf16 v[126:129], v[54:57], v[180:183], v[126:129]
	v_mfma_f32_16x16x32_bf16 v[122:125], v[62:65], v[180:183], v[122:125]
	v_mfma_f32_16x16x32_bf16 v[110:113], v[54:57], v[188:191], v[110:113]
	v_mfma_f32_16x16x32_bf16 v[106:109], v[62:65], v[188:191], v[106:109]
	v_mfma_f32_16x16x32_bf16 v[94:97], v[54:57], v[196:199], v[94:97]
	v_mfma_f32_16x16x32_bf16 v[90:93], v[62:65], v[196:199], v[90:93]
	v_mfma_f32_16x16x32_bf16 v[134:137], v[146:149], v[162:165], v[134:137]
	v_mfma_f32_16x16x32_bf16 v[130:133], v[154:157], v[162:165], v[130:133]
	v_mfma_f32_16x16x32_bf16 v[118:121], v[146:149], v[170:173], v[118:121]
	v_mfma_f32_16x16x32_bf16 v[114:117], v[154:157], v[170:173], v[114:117]
	v_mfma_f32_16x16x32_bf16 v[102:105], v[146:149], v[184:187], v[102:105]
	v_mfma_f32_16x16x32_bf16 v[98:101], v[154:157], v[184:187], v[98:101]
	v_mfma_f32_16x16x32_bf16 v[86:89], v[146:149], v[192:195], v[86:89]
	v_mfma_f32_16x16x32_bf16 v[82:85], v[154:157], v[192:195], v[82:85]
	v_mfma_f32_16x16x32_bf16 v[134:137], v[150:153], v[166:169], v[134:137]
	v_mfma_f32_16x16x32_bf16 v[130:133], v[158:161], v[166:169], v[130:133]
	v_mfma_f32_16x16x32_bf16 v[118:121], v[150:153], v[180:183], v[118:121]
	v_mfma_f32_16x16x32_bf16 v[114:117], v[158:161], v[180:183], v[114:117]
	v_mfma_f32_16x16x32_bf16 v[102:105], v[150:153], v[188:191], v[102:105]
	v_mfma_f32_16x16x32_bf16 v[98:101], v[158:161], v[188:191], v[98:101]
	v_mfma_f32_16x16x32_bf16 v[86:89], v[150:153], v[196:199], v[86:89]
	v_mfma_f32_16x16x32_bf16 v[82:85], v[158:161], v[196:199], v[82:85]
	s_barrier
	s_setprio 0
	s_add_i32 s34, s34, s13
	v_lshl_add_u64 v[200:201], s[6:7], 0, v[0:1]
	s_mov_b32 m0, s34
	ds_read_b128 v[162:165], v207 offset:16384
	ds_read_b128 v[166:169], v207 offset:17408
	ds_read_b128 v[170:173], v207 offset:18432
	ds_read_b128 v[180:183], v207 offset:19456
	ds_read_b128 v[184:187], v207 offset:20480
	ds_read_b128 v[188:191], v207 offset:21504
	ds_read_b128 v[192:195], v207 offset:22528
	ds_read_b128 v[196:199], v207 offset:23552
	global_load_lds_dwordx4 v[200:201], off
	s_add_i32 m0, s34, 0x2000
	s_add_u32 s46, s6, 0x80000
	v_lshl_add_u64 v[202:203], s[6:7], 0, v[174:175]
	s_addc_u32 s47, s7, 0
	s_add_i32 s34, s35, s13
	global_load_lds_dwordx4 v[202:203], off
	v_lshl_add_u64 v[208:209], s[46:47], 0, v[0:1]
	s_mov_b32 m0, s34
	v_lshl_add_u64 v[210:211], s[94:95], 0, v[174:175]
	global_load_lds_dwordx4 v[208:209], off
	s_add_i32 m0, s34, 0x2000
	v_lshl_add_u64 v[208:209], s[46:47], 0, v[174:175]
	global_load_lds_dwordx4 v[208:209], off
	s_mov_b32 m0, s66
	v_lshl_add_u64 v[208:209], s[94:95], 0, v[0:1]
	global_load_lds_dwordx4 v[208:209], off
	s_mov_b32 m0, s67
	s_nop 0
	global_load_lds_dwordx4 v[210:211], off
	s_setprio 1
	s_waitcnt vmcnt(8) lgkmcnt(0)
	s_barrier
; #define PG8_STAGE(bufoff, gbase, voff) do { _Pragma("unroll") for (int _i = 0; _i < 2; ++_i) \
;         __builtin_amdgcn_global_load_lds((const unsigned*)((const char*)(gbase) + (voff)[_i]), (LAS unsigned*)(lds + (bufoff) + ldsw + _i * 8192), 16, 0, 0); } while (0)
; #define PG8_LDA(dst, b, h) do { _Pragma("unroll") for (int m = 0; m < 4; ++m) _Pragma("unroll") for (int k = 0; k < 2; ++k) dst[m][k] = *(const LAS bf16x8*)(lds + PG8_SA(b, h) + aoff + m * 2048 + k * 1024); } while (0)
; #define PG8_LDB(dst, b, h) do { _Pragma("unroll") for (int n = 0; n < 2; ++n) _Pragma("unroll") for (int k = 0; k < 2; ++k) dst[n][k] = *(const LAS bf16x8*)(lds + PG8_SB(b, h) + boff + n * 2048 + k * 1024); } while (0)
; #define PG8_MMA(ai, bj, At, Bt) do { __builtin_amdgcn_s_setprio(1); _Pragma("unroll") for (int m = 0; m < 4; ++m) _Pragma("unroll") for (int n = 0; n < 2; ++n) _Pragma("unroll") for (int k = 0; k < 2; ++k) \
;         acc[ai][bj][m][n] = __builtin_amdgcn_mfma_f32_16x16x32_bf16(Bt[n][k], At[m][k], acc[ai][bj][m][n], 0, 0, 0); __builtin_amdgcn_s_setprio(0); } while (0)
; #define PG8_WAIT_V(n) asm volatile("s_waitcnt vmcnt(" #n ")" ::: "memory")
; #define PG8_WAIT_L(n) asm volatile("s_waitcnt lgkmcnt(" #n ")" ::: "memory")
; #define PG8_BAR __builtin_amdgcn_s_barrier()
; #define PG8_SCHED __builtin_amdgcn_sched_barrier(0)
; template <class Epi, int AMODE>
; __device__ __forceinline__ void gemm_phase(LAS unsigned char* lds, const Gemm g, const StaticOrder& S, const Epi& E, int stagger_us, int tid_in) {
;     ...
;             PG8_WAIT_V(8); PG8_WAIT_L(0); PG8_BAR; PG8_MMA(1, 0, At, B0); PG8_MMA(1, 1, At, B1); PG8_BAR; PG8_SCHED;
;             PG8_LDB(B0, 1, 0); PG8_LDB(B1, 1, 1); PG8_SCHED; PG8_LDA(At, 1, 0); PG8_STAGE(PG8_SA(0, 1), a2 + hstepA, voffA);
;             PG8_WAIT_V(8); PG8_WAIT_L(0); PG8_BAR; PG8_MMA(0, 0, At, B0); PG8_MMA(0, 1, At, B1); PG8_BAR; PG8_SCHED;
	v_mfma_f32_16x16x32_bf16 v[78:81], v[50:53], v[162:165], v[78:81]
	v_mfma_f32_16x16x32_bf16 v[74:77], v[58:61], v[162:165], v[74:77]
	v_mfma_f32_16x16x32_bf16 v[46:49], v[50:53], v[170:173], v[46:49]
	v_mfma_f32_16x16x32_bf16 v[42:45], v[58:61], v[170:173], v[42:45]
	v_mfma_f32_16x16x32_bf16 v[30:33], v[50:53], v[184:187], v[30:33]
	v_mfma_f32_16x16x32_bf16 v[26:29], v[58:61], v[184:187], v[26:29]
	v_mfma_f32_16x16x32_bf16 v[14:17], v[50:53], v[192:195], v[14:17]
	v_mfma_f32_16x16x32_bf16 v[10:13], v[58:61], v[192:195], v[10:13]
	v_mfma_f32_16x16x32_bf16 v[78:81], v[54:57], v[166:169], v[78:81]
	v_mfma_f32_16x16x32_bf16 v[74:77], v[62:65], v[166:169], v[74:77]
	v_mfma_f32_16x16x32_bf16 v[46:49], v[54:57], v[180:183], v[46:49]
	v_mfma_f32_16x16x32_bf16 v[42:45], v[62:65], v[180:183], v[42:45]
	v_mfma_f32_16x16x32_bf16 v[30:33], v[54:57], v[188:191], v[30:33]
	v_mfma_f32_16x16x32_bf16 v[26:29], v[62:65], v[188:191], v[26:29]
	v_mfma_f32_16x16x32_bf16 v[14:17], v[54:57], v[196:199], v[14:17]
	v_mfma_f32_16x16x32_bf16 v[10:13], v[62:65], v[196:199], v[10:13]
	v_mfma_f32_16x16x32_bf16 v[38:41], v[146:149], v[170:173], v[38:41]
	v_mfma_f32_16x16x32_bf16 v[34:37], v[154:157], v[170:173], v[34:37]
	v_mfma_f32_16x16x32_bf16 v[22:25], v[146:149], v[184:187], v[22:25]
	v_mfma_f32_16x16x32_bf16 v[18:21], v[154:157], v[184:187], v[18:21]
	v_mfma_f32_16x16x32_bf16 v[6:9], v[146:149], v[192:195], v[6:9]
	v_mfma_f32_16x16x32_bf16 v[2:5], v[154:157], v[192:195], v[2:5]
	v_mfma_f32_16x16x32_bf16 v[50:53], v[146:149], v[162:165], v[70:73]
	v_mfma_f32_16x16x32_bf16 v[54:57], v[154:157], v[162:165], v[66:69]
	v_mfma_f32_16x16x32_bf16 v[38:41], v[150:153], v[180:183], v[38:41]
	v_mfma_f32_16x16x32_bf16 v[34:37], v[158:161], v[180:183], v[34:37]
	v_mfma_f32_16x16x32_bf16 v[22:25], v[150:153], v[188:191], v[22:25]
	v_mfma_f32_16x16x32_bf16 v[18:21], v[158:161], v[188:191], v[18:21]
	v_mfma_f32_16x16x32_bf16 v[6:9], v[150:153], v[196:199], v[6:9]
	v_mfma_f32_16x16x32_bf16 v[2:5], v[158:161], v[196:199], v[2:5]
	v_mfma_f32_16x16x32_bf16 v[50:53], v[150:153], v[166:169], v[50:53]
	v_mfma_f32_16x16x32_bf16 v[54:57], v[158:161], v[166:169], v[54:57]
	s_barrier
	s_setprio 0
	s_add_i32 s34, 0, 0x18000
	s_add_i32 s35, 0, 0x1c000
	v_add_u32_e32 v70, s34, v205
	v_add_u32_e32 v158, s35, v205
	ds_read_b128 v[58:61], v70
	ds_read_b128 v[62:65], v70 offset:1024
	ds_read_b128 v[66:69], v70 offset:2048
	ds_read_b128 v[70:73], v70 offset:3072
	ds_read_b128 v[146:149], v158
	ds_read_b128 v[150:153], v158 offset:1024
	ds_read_b128 v[154:157], v158 offset:2048
	ds_read_b128 v[158:161], v158 offset:3072
	s_add_u32 s46, s94, 0x80000
	s_addc_u32 s47, s95, 0
	s_mov_b32 m0, s69
	v_lshl_add_u64 v[212:213], s[46:47], 0, v[0:1]
	ds_read_b128 v[162:165], v207 offset:32768
	ds_read_b128 v[166:169], v207 offset:33792
	ds_read_b128 v[170:173], v207 offset:34816
	ds_read_b128 v[180:183], v207 offset:35840
	ds_read_b128 v[184:187], v207 offset:36864
	ds_read_b128 v[188:191], v207 offset:37888
	ds_read_b128 v[192:195], v207 offset:38912
	ds_read_b128 v[196:199], v207 offset:39936
	global_load_lds_dwordx4 v[212:213], off
	s_mov_b32 m0, s72
	v_lshl_add_u64 v[212:213], s[46:47], 0, v[174:175]
	global_load_lds_dwordx4 v[212:213], off
	s_setprio 1
	s_waitcnt vmcnt(8) lgkmcnt(0)
	s_barrier
	v_mfma_f32_16x16x32_bf16 v[142:145], v[58:61], v[162:165], v[142:145]
	v_mfma_f32_16x16x32_bf16 v[138:141], v[66:69], v[162:165], v[138:141]
	v_mfma_f32_16x16x32_bf16 v[126:129], v[58:61], v[170:173], v[126:129]
	v_mfma_f32_16x16x32_bf16 v[122:125], v[66:69], v[170:173], v[122:125]
	v_mfma_f32_16x16x32_bf16 v[110:113], v[58:61], v[184:187], v[110:113]
	v_mfma_f32_16x16x32_bf16 v[106:109], v[66:69], v[184:187], v[106:109]
	v_mfma_f32_16x16x32_bf16 v[94:97], v[58:61], v[192:195], v[94:97]
	v_mfma_f32_16x16x32_bf16 v[90:93], v[66:69], v[192:195], v[90:93]
	v_mfma_f32_16x16x32_bf16 v[142:145], v[62:65], v[166:169], v[142:145]
	v_mfma_f32_16x16x32_bf16 v[138:141], v[70:73], v[166:169], v[138:141]
	v_mfma_f32_16x16x32_bf16 v[126:129], v[62:65], v[180:183], v[126:129]
	v_mfma_f32_16x16x32_bf16 v[122:125], v[70:73], v[180:183], v[122:125]
	v_mfma_f32_16x16x32_bf16 v[110:113], v[62:65], v[188:191], v[110:113]
	v_mfma_f32_16x16x32_bf16 v[106:109], v[70:73], v[188:191], v[106:109]
	v_mfma_f32_16x16x32_bf16 v[94:97], v[62:65], v[196:199], v[94:97]
	v_mfma_f32_16x16x32_bf16 v[90:93], v[70:73], v[196:199], v[90:93]
	v_mfma_f32_16x16x32_bf16 v[134:137], v[146:149], v[162:165], v[134:137]
	v_mfma_f32_16x16x32_bf16 v[130:133], v[154:157], v[162:165], v[130:133]
	v_mfma_f32_16x16x32_bf16 v[118:121], v[146:149], v[170:173], v[118:121]
	v_mfma_f32_16x16x32_bf16 v[114:117], v[154:157], v[170:173], v[114:117]
	v_mfma_f32_16x16x32_bf16 v[102:105], v[146:149], v[184:187], v[102:105]
	v_mfma_f32_16x16x32_bf16 v[98:101], v[154:157], v[184:187], v[98:101]
	v_mfma_f32_16x16x32_bf16 v[86:89], v[146:149], v[192:195], v[86:89]
	v_mfma_f32_16x16x32_bf16 v[82:85], v[154:157], v[192:195], v[82:85]
	v_mfma_f32_16x16x32_bf16 v[134:137], v[150:153], v[166:169], v[134:137]
	v_mfma_f32_16x16x32_bf16 v[130:133], v[158:161], v[166:169], v[130:133]
	v_mfma_f32_16x16x32_bf16 v[118:121], v[150:153], v[180:183], v[118:121]
	v_mfma_f32_16x16x32_bf16 v[114:117], v[158:161], v[180:183], v[114:117]
	v_mfma_f32_16x16x32_bf16 v[102:105], v[150:153], v[188:191], v[102:105]
	v_mfma_f32_16x16x32_bf16 v[98:101], v[158:161], v[188:191], v[98:101]
	v_mfma_f32_16x16x32_bf16 v[86:89], v[150:153], v[196:199], v[86:89]
	v_mfma_f32_16x16x32_bf16 v[82:85], v[158:161], v[196:199], v[82:85]
	s_barrier
; #define PG8_STAGE(bufoff, gbase, voff) do { _Pragma("unroll") for (int _i = 0; _i < 2; ++_i) \
;         __builtin_amdgcn_global_load_lds((const unsigned*)((const char*)(gbase) + (voff)[_i]), (LAS unsigned*)(lds + (bufoff) + ldsw + _i * 8192), 16, 0, 0); } while (0)
; #define PG8_LDA(dst, b, h) do { _Pragma("unroll") for (int m = 0; m < 4; ++m) _Pragma("unroll") for (int k = 0; k < 2; ++k) dst[m][k] = *(const LAS bf16x8*)(lds + PG8_SA(b, h) + aoff + m * 2048 + k * 1024); } while (0)
; #define PG8_MMA(ai, bj, At, Bt) do { __builtin_amdgcn_s_setprio(1); _Pragma("unroll") for (int m = 0; m < 4; ++m) _Pragma("unroll") for (int n = 0; n < 2; ++n) _Pragma("unroll") for (int k = 0; k < 2; ++k) \
;         acc[ai][bj][m][n] = __builtin_amdgcn_mfma_f32_16x16x32_bf16(Bt[n][k], At[m][k], acc[ai][bj][m][n], 0, 0, 0); __builtin_amdgcn_s_setprio(0); } while (0)
; #define PG8_WAIT_V(n) asm volatile("s_waitcnt vmcnt(" #n ")" ::: "memory")
; #define PG8_WAIT_L(n) asm volatile("s_waitcnt lgkmcnt(" #n ")" ::: "memory")
; #define PG8_BAR __builtin_amdgcn_s_barrier()
; #define PG8_SCHED __builtin_amdgcn_sched_barrier(0)
; template <class Epi, int AMODE>
; __device__ __forceinline__ void gemm_phase(LAS unsigned char* lds, const Gemm g, const StaticOrder& S, const Epi& E, int stagger_us, int tid_in) {
;     ...
;             PG8_LDA(At, 1, 1); PG8_STAGE(PG8_SB(1, 0), b3, voffB); PG8_STAGE(PG8_SB(1, 1), b3 + hstepB, voffB); PG8_STAGE(PG8_SA(1, 0), a3, voffA);
;             PG8_WAIT_V(8); PG8_WAIT_L(0); PG8_BAR; PG8_MMA(1, 0, At, B0); PG8_MMA(1, 1, At, B1); PG8_BAR; PG8_SCHED;
;         }
;         if (wr == 0) PG8_BAR;
	s_setprio 0
	s_add_i32 s34, s34, s13
	v_lshl_add_u64 v[200:201], v[200:201], 0, s[74:75]
	s_mov_b32 m0, s34
	ds_read_b128 v[162:165], v207 offset:49152
	ds_read_b128 v[166:169], v207 offset:50176
	ds_read_b128 v[170:173], v207 offset:51200
	ds_read_b128 v[180:183], v207 offset:52224
	ds_read_b128 v[184:187], v207 offset:53248
	ds_read_b128 v[188:191], v207 offset:54272
	ds_read_b128 v[192:195], v207 offset:55296
	ds_read_b128 v[196:199], v207 offset:56320
	global_load_lds_dwordx4 v[200:201], off
	s_add_i32 m0, s34, 0x2000
	s_add_u32 s6, s6, 0x80080
	v_lshl_add_u64 v[200:201], v[202:203], 0, s[74:75]
	s_addc_u32 s7, s7, 0
	s_add_i32 s34, s35, s13
	global_load_lds_dwordx4 v[200:201], off
	s_mov_b32 m0, s34
	v_lshl_add_u64 v[200:201], s[6:7], 0, v[0:1]
	global_load_lds_dwordx4 v[200:201], off
	s_add_i32 m0, s34, 0x2000
	v_lshl_add_u64 v[200:201], s[6:7], 0, v[174:175]
	global_load_lds_dwordx4 v[200:201], off
	s_mov_b32 m0, s91
	v_lshl_add_u64 v[200:201], v[208:209], 0, s[74:75]
	global_load_lds_dwordx4 v[200:201], off
	s_mov_b32 m0, s96
	v_lshl_add_u64 v[200:201], v[210:211], 0, s[74:75]
	global_load_lds_dwordx4 v[200:201], off
	s_setprio 1
	s_waitcnt vmcnt(8) lgkmcnt(0)
	s_barrier
	v_mfma_f32_16x16x32_bf16 v[78:81], v[58:61], v[162:165], v[78:81]
	v_mfma_f32_16x16x32_bf16 v[74:77], v[66:69], v[162:165], v[74:77]
	v_mfma_f32_16x16x32_bf16 v[46:49], v[58:61], v[170:173], v[46:49]
	v_mfma_f32_16x16x32_bf16 v[42:45], v[66:69], v[170:173], v[42:45]
	v_mfma_f32_16x16x32_bf16 v[30:33], v[58:61], v[184:187], v[30:33]
	v_mfma_f32_16x16x32_bf16 v[26:29], v[66:69], v[184:187], v[26:29]
	v_mfma_f32_16x16x32_bf16 v[14:17], v[58:61], v[192:195], v[14:17]
	v_mfma_f32_16x16x32_bf16 v[10:13], v[66:69], v[192:195], v[10:13]
	v_mfma_f32_16x16x32_bf16 v[78:81], v[62:65], v[166:169], v[78:81]
	v_mfma_f32_16x16x32_bf16 v[74:77], v[70:73], v[166:169], v[74:77]
	v_mfma_f32_16x16x32_bf16 v[46:49], v[62:65], v[180:183], v[46:49]
	v_mfma_f32_16x16x32_bf16 v[42:45], v[70:73], v[180:183], v[42:45]
	v_mfma_f32_16x16x32_bf16 v[30:33], v[62:65], v[188:191], v[30:33]
	v_mfma_f32_16x16x32_bf16 v[26:29], v[70:73], v[188:191], v[26:29]
	v_mfma_f32_16x16x32_bf16 v[14:17], v[62:65], v[196:199], v[14:17]
	v_mfma_f32_16x16x32_bf16 v[10:13], v[70:73], v[196:199], v[10:13]
	v_mfma_f32_16x16x32_bf16 v[50:53], v[146:149], v[162:165], v[50:53]
	v_mfma_f32_16x16x32_bf16 v[70:73], v[150:153], v[166:169], v[50:53]
	v_mfma_f32_16x16x32_bf16 v[50:53], v[154:157], v[162:165], v[54:57]
	v_mfma_f32_16x16x32_bf16 v[38:41], v[146:149], v[170:173], v[38:41]
	v_mfma_f32_16x16x32_bf16 v[34:37], v[154:157], v[170:173], v[34:37]
	v_mfma_f32_16x16x32_bf16 v[22:25], v[146:149], v[184:187], v[22:25]
	v_mfma_f32_16x16x32_bf16 v[18:21], v[154:157], v[184:187], v[18:21]
	v_mfma_f32_16x16x32_bf16 v[6:9], v[146:149], v[192:195], v[6:9]
	v_mfma_f32_16x16x32_bf16 v[2:5], v[154:157], v[192:195], v[2:5]
	v_mfma_f32_16x16x32_bf16 v[66:69], v[158:161], v[166:169], v[50:53]
	v_mfma_f32_16x16x32_bf16 v[38:41], v[150:153], v[180:183], v[38:41]
	v_mfma_f32_16x16x32_bf16 v[34:37], v[158:161], v[180:183], v[34:37]
	v_mfma_f32_16x16x32_bf16 v[22:25], v[150:153], v[188:191], v[22:25]
	v_mfma_f32_16x16x32_bf16 v[18:21], v[158:161], v[188:191], v[18:21]
	v_mfma_f32_16x16x32_bf16 v[6:9], v[150:153], v[196:199], v[6:9]
	v_mfma_f32_16x16x32_bf16 v[2:5], v[158:161], v[196:199], v[2:5]
	s_barrier
	s_setprio 0
	s_add_i32 s31, s31, 2
	s_add_u32 s29, s29, 0x100
	s_addc_u32 s30, s30, 0
	s_cmp_gt_u32 s31, 29
	s_mov_b64 s[46:47], s[4:5]
	s_cbranch_scc0 .LBB0_1199
	s_and_b64 vcc, exec, s[56:57]
	s_cbranch_vccz .LBB0_1202
	s_barrier

; #define PG8_STAGE(bufoff, gbase, voff) do { _Pragma("unroll") for (int _i = 0; _i < 2; ++_i) \
;         __builtin_amdgcn_global_load_lds((const unsigned*)((const char*)(gbase) + (voff)[_i]), (LAS unsigned*)(lds + (bufoff) + ldsw + _i * 8192), 16, 0, 0); } while (0)
; #define PG8_LDA(dst, b, h) do { _Pragma("unroll") for (int m = 0; m < 4; ++m) _Pragma("unroll") for (int k = 0; k < 2; ++k) dst[m][k] = *(const LAS bf16x8*)(lds + PG8_SA(b, h) + aoff + m * 2048 + k * 1024); } while (0)
; #define PG8_LDB(dst, b, h) do { _Pragma("unroll") for (int n = 0; n < 2; ++n) _Pragma("unroll") for (int k = 0; k < 2; ++k) dst[n][k] = *(const LAS bf16x8*)(lds + PG8_SB(b, h) + boff + n * 2048 + k * 1024); } while (0)
; #define PG8_MMA(ai, bj, At, Bt) do { __builtin_amdgcn_s_setprio(1); _Pragma("unroll") for (int m = 0; m < 4; ++m) _Pragma("unroll") for (int n = 0; n < 2; ++n) _Pragma("unroll") for (int k = 0; k < 2; ++k) \
;         acc[ai][bj][m][n] = __builtin_amdgcn_mfma_f32_16x16x32_bf16(Bt[n][k], At[m][k], acc[ai][bj][m][n], 0, 0, 0); __builtin_amdgcn_s_setprio(0); } while (0)
; template <class Epi, int AMODE>
; __device__ __forceinline__ void gemm_phase(LAS unsigned char* lds, const Gemm g, const StaticOrder& S, const Epi& E, int stagger_us, int tid_in) {
;     ...
;             PG8_LDB(B0, 0, 0); PG8_LDB(B1, 0, 1); PG8_SCHED; PG8_LDA(At, 0, 0); PG8_STAGE(PG8_SA(1, 1), a1 + hstepA, voffA);
;             PG8_WAIT_V(8); PG8_WAIT_L(0); PG8_BAR; PG8_MMA(0, 0, At, B0); PG8_MMA(0, 1, At, B1); PG8_BAR; PG8_SCHED;
;     __device__ __forceinline__ void operator()(f32x4 (&acc)[2][2][4][2], const Unit& u, int wr, int wc, int fr, int fq) const {
;     ...
;         {
;             const int tq = tok0 + 8 * fr; const int tA = tq < 0 ? 0 : (tq > TOK - 1 ? TOK - 1 : tq), tB = (tq + 7) > TOK - 1 ? TOK - 1 : (tq + 7);
;             const int bA = batch_of(tA), bB = batch_of(tB); const bool same = __all(bA == bB);
;             const float* bp0 = bias + 256 * u.pn + 32 * wc + 8 * fq;
;             f32x4 bvA[2][2]; float sq[8];
; #pragma unroll
;             for (int am = 0; am < 8; ++am) { int tok = tq + am; tok = tok < 0 ? 0 : (tok > TOK - 1 ? TOK - 1 : tok); sq[am] = LDG(float, ssq + tok); }
; #pragma unroll
;             for (int bj = 0; bj < 2; ++bj)
; #pragma unroll
;                 for (int n = 0; n < 2; ++n) bvA[bj][n] = LDG(f32x4, bp0 + (size_t)bA * (2 * DFF) + bj * HALF + 4 * n);
.LBB0_1298:
	s_ashr_i32 s47, s46, 31
	s_lshl_b64 s[6:7], s[46:47], 20
	s_add_u32 s96, s9, s6
	s_addc_u32 s97, s72, s7
	s_and_b64 s[6:7], s[42:43], exec
	s_cselect_b32 s27, s97, s5
	s_cselect_b32 s28, s96, s4
	s_add_u32 s29, s4, 0x100
	v_mov_b32_e32 v2, 0
	s_addc_u32 s30, s5, 0
	s_mov_b32 s31, -2
	s_mul_i32 s6, s26, 0xfc
	v_add_u32_e32 v222, s6, v197
	v_med3_i32 v240, v222, 0, v238
	v_add_u32_e32 v241, 0xffffe000, v240
	v_lshrrev_b32_e32 v241, 12, v241
	v_add_u32_e32 v241, 4, v241
	v_lshrrev_b32_e32 v242, 11, v240
	v_mov_b32_e32 v243, 0x2000
	v_cmp_gt_i32_e64 s[6:7], v243, v222
	s_nop 1
	v_cndmask_b32_e64 v241, v241, v242, s[6:7]
	s_lshl_b32 s6, s92, 8
	s_ashr_i32 s7, s6, 31
	v_lshl_add_u64 v[236:237], s[6:7], 2, v[184:185]
	v_mad_u64_u32 v[236:237], s[6:7], v241, s15, v[236:237]
	v_med3_i32 v224, v222, 0, v238
	v_lshlrev_b32_e32 v224, 2, v224
	global_load_dword v224, v224, s[56:57]
	v_add_u32_e32 v228, 1, v222
	v_med3_i32 v228, v228, 0, v238
	v_lshlrev_b32_e32 v228, 2, v228
	global_load_dword v228, v228, s[56:57]
	v_add_u32_e32 v231, 2, v222
	v_med3_i32 v231, v231, 0, v238
	v_lshlrev_b32_e32 v231, 2, v231
	global_load_dword v231, v231, s[56:57]
	v_add_u32_e32 v233, 3, v222
	v_med3_i32 v233, v233, 0, v238
	v_lshlrev_b32_e32 v233, 2, v233
	global_load_dword v233, v233, s[56:57]
	v_add_u32_e32 v234, 4, v222
	v_med3_i32 v234, v234, 0, v238
	v_lshlrev_b32_e32 v234, 2, v234
	global_load_dword v234, v234, s[56:57]
	v_add_u32_e32 v239, 5, v222
	v_med3_i32 v239, v239, 0, v238
	v_lshlrev_b32_e32 v239, 2, v239
	global_load_dword v239, v239, s[56:57]
	v_add_u32_e32 v252, 6, v222
	v_med3_i32 v252, v252, 0, v238
	v_lshlrev_b32_e32 v252, 2, v252
	global_load_dword v252, v252, s[56:57]
	v_add_u32_e32 v253, 7, v222
	v_med3_i32 v253, v253, 0, v238
	v_lshlrev_b32_e32 v253, 2, v253
	global_load_dword v253, v253, s[56:57]
	global_load_dwordx4 v[240:243], v[236:237], off
	global_load_dwordx4 v[244:247], v[236:237], off offset:16
	global_load_dwordx4 v[248:251], v[236:237], off offset:512
	global_load_dwordx2 v[222:223], v[236:237], off offset:528
	s_nop 0
	global_load_dwordx2 v[236:237], v[236:237], off offset:536
	s_add_u32 s4, s44, 0x100
	s_addc_u32 s5, s45, 0
	s_add_i32 s34, 0, 0x10000
	s_cmp_eq_u32 s31, 28
	s_cselect_b32 s43, s95, s5
	s_cselect_b32 s42, s94, s4
	s_cselect_b32 s7, s27, s30
	s_cselect_b32 s6, s28, s29
	s_add_i32 s35, 0, 0x14000
	v_add_u32_e32 v142, s34, v196
	v_add_u32_e32 v158, s35, v196
	ds_read_b128 v[130:133], v142
	ds_read_b128 v[134:137], v142 offset:1024
	ds_read_b128 v[138:141], v142 offset:2048
	ds_read_b128 v[142:145], v142 offset:3072
	ds_read_b128 v[146:149], v158
	ds_read_b128 v[150:153], v158 offset:1024
	ds_read_b128 v[154:157], v158 offset:2048
	ds_read_b128 v[158:161], v158 offset:3072
	v_lshl_add_u64 v[194:195], s[44:45], 0, v[186:187]
	s_add_i32 m0, s93, 0xc000
	ds_read_b128 v[162:165], v201
	ds_read_b128 v[166:169], v201 offset:1024
	ds_read_b128 v[170:173], v201 offset:2048
	ds_read_b128 v[174:177], v201 offset:3072
	ds_read_b128 v[190:193], v201 offset:4096
	ds_read_b128 v[202:205], v201 offset:5120
	ds_read_b128 v[206:209], v201 offset:6144
	ds_read_b128 v[210:213], v201 offset:7168
	global_load_lds_dwordx4 v[194:195], off
	s_add_i32 m0, s93, 0xe000
	v_lshl_add_u64 v[194:195], s[44:45], 0, v[188:189]
	global_load_lds_dwordx4 v[194:195], off
	s_setprio 1
	s_waitcnt lgkmcnt(0)
	s_barrier
	v_mfma_f32_16x16x32_bf16 v[126:129], v[130:133], v[162:165], 0
	v_mfma_f32_16x16x32_bf16 v[122:125], v[138:141], v[162:165], 0
	v_mfma_f32_16x16x32_bf16 v[118:121], v[130:133], v[170:173], 0
	v_mfma_f32_16x16x32_bf16 v[114:117], v[138:141], v[170:173], 0
	v_mfma_f32_16x16x32_bf16 v[110:113], v[130:133], v[190:193], 0
	v_mfma_f32_16x16x32_bf16 v[102:105], v[138:141], v[190:193], 0
	v_mfma_f32_16x16x32_bf16 v[90:93], v[130:133], v[206:209], 0
	v_mfma_f32_16x16x32_bf16 v[82:85], v[138:141], v[206:209], 0
	v_mfma_f32_16x16x32_bf16 v[126:129], v[134:137], v[166:169], v[126:129]
	v_mfma_f32_16x16x32_bf16 v[122:125], v[142:145], v[166:169], v[122:125]
	v_mfma_f32_16x16x32_bf16 v[118:121], v[134:137], v[174:177], v[118:121]
	v_mfma_f32_16x16x32_bf16 v[114:117], v[142:145], v[174:177], v[114:117]
	v_mfma_f32_16x16x32_bf16 v[110:113], v[134:137], v[202:205], v[110:113]
	v_mfma_f32_16x16x32_bf16 v[102:105], v[142:145], v[202:205], v[102:105]
	v_mfma_f32_16x16x32_bf16 v[90:93], v[134:137], v[210:213], v[90:93]
	v_mfma_f32_16x16x32_bf16 v[82:85], v[142:145], v[210:213], v[82:85]
	v_mfma_f32_16x16x32_bf16 v[106:109], v[146:149], v[162:165], 0
	v_mfma_f32_16x16x32_bf16 v[98:101], v[154:157], v[162:165], 0
	v_mfma_f32_16x16x32_bf16 v[94:97], v[146:149], v[170:173], 0
	v_mfma_f32_16x16x32_bf16 v[86:89], v[154:157], v[170:173], 0
	v_mfma_f32_16x16x32_bf16 v[70:73], v[146:149], v[190:193], 0
	v_mfma_f32_16x16x32_bf16 v[62:65], v[154:157], v[190:193], 0
	v_mfma_f32_16x16x32_bf16 v[78:81], v[146:149], v[206:209], 0
	v_mfma_f32_16x16x32_bf16 v[66:69], v[154:157], v[206:209], 0
	v_mfma_f32_16x16x32_bf16 v[106:109], v[150:153], v[166:169], v[106:109]
	v_mfma_f32_16x16x32_bf16 v[98:101], v[158:161], v[166:169], v[98:101]
	v_mfma_f32_16x16x32_bf16 v[94:97], v[150:153], v[174:177], v[94:97]
	v_mfma_f32_16x16x32_bf16 v[86:89], v[158:161], v[174:177], v[86:89]
	v_mfma_f32_16x16x32_bf16 v[70:73], v[150:153], v[202:205], v[70:73]
	v_mfma_f32_16x16x32_bf16 v[62:65], v[158:161], v[202:205], v[62:65]
	v_mfma_f32_16x16x32_bf16 v[78:81], v[150:153], v[210:213], v[78:81]
	v_mfma_f32_16x16x32_bf16 v[66:69], v[158:161], v[210:213], v[66:69]
	s_barrier
; #define PG8_STAGE(bufoff, gbase, voff) do { _Pragma("unroll") for (int _i = 0; _i < 2; ++_i) \
;         __builtin_amdgcn_global_load_lds((const unsigned*)((const char*)(gbase) + (voff)[_i]), (LAS unsigned*)(lds + (bufoff) + ldsw + _i * 8192), 16, 0, 0); } while (0)
; #define PG8_LDA(dst, b, h) do { _Pragma("unroll") for (int m = 0; m < 4; ++m) _Pragma("unroll") for (int k = 0; k < 2; ++k) dst[m][k] = *(const LAS bf16x8*)(lds + PG8_SA(b, h) + aoff + m * 2048 + k * 1024); } while (0)
; #define PG8_LDB(dst, b, h) do { _Pragma("unroll") for (int n = 0; n < 2; ++n) _Pragma("unroll") for (int k = 0; k < 2; ++k) dst[n][k] = *(const LAS bf16x8*)(lds + PG8_SB(b, h) + boff + n * 2048 + k * 1024); } while (0)
; #define PG8_MMA(ai, bj, At, Bt) do { __builtin_amdgcn_s_setprio(1); _Pragma("unroll") for (int m = 0; m < 4; ++m) _Pragma("unroll") for (int n = 0; n < 2; ++n) _Pragma("unroll") for (int k = 0; k < 2; ++k) \
;         acc[ai][bj][m][n] = __builtin_amdgcn_mfma_f32_16x16x32_bf16(Bt[n][k], At[m][k], acc[ai][bj][m][n], 0, 0, 0); __builtin_amdgcn_s_setprio(0); } while (0)
; #define PG8_WAIT_V(n) asm volatile("s_waitcnt vmcnt(" #n ")" ::: "memory")
; #define PG8_WAIT_L(n) asm volatile("s_waitcnt lgkmcnt(" #n ")" ::: "memory")
; #define PG8_BAR __builtin_amdgcn_s_barrier()
; #define PG8_SCHED __builtin_amdgcn_sched_barrier(0)
; template <class Epi, int AMODE>
; __device__ __forceinline__ void gemm_phase(LAS unsigned char* lds, const Gemm g, const StaticOrder& S, const Epi& E, int stagger_us, int tid_in) {
;     ...
;             PG8_LDA(At, 0, 1); PG8_STAGE(PG8_SB(0, 0), b2, voffB); PG8_STAGE(PG8_SB(0, 1), b2 + hstepB, voffB); PG8_STAGE(PG8_SA(0, 0), a2, voffA);
;             PG8_WAIT_V(8); PG8_WAIT_L(0); PG8_BAR; PG8_MMA(1, 0, At, B0); PG8_MMA(1, 1, At, B1); PG8_BAR; PG8_SCHED;
;             PG8_LDB(B0, 1, 0); PG8_LDB(B1, 1, 1); PG8_SCHED; PG8_LDA(At, 1, 0); PG8_STAGE(PG8_SA(0, 1), a2 + hstepA, voffA);
;             PG8_WAIT_V(8); PG8_WAIT_L(0); PG8_BAR; PG8_MMA(0, 0, At, B0); PG8_MMA(0, 1, At, B1); PG8_BAR; PG8_SCHED;
	s_setprio 0
	s_add_i32 s34, s34, s91
	v_lshl_add_u64 v[194:195], s[6:7], 0, v[0:1]
	s_mov_b32 m0, s34
	ds_read_b128 v[162:165], v201 offset:16384
	ds_read_b128 v[166:169], v201 offset:17408
	ds_read_b128 v[170:173], v201 offset:18432
	ds_read_b128 v[174:177], v201 offset:19456
	ds_read_b128 v[190:193], v201 offset:20480
	ds_read_b128 v[202:205], v201 offset:21504
	ds_read_b128 v[206:209], v201 offset:22528
	ds_read_b128 v[210:213], v201 offset:23552
	global_load_lds_dwordx4 v[194:195], off
	s_add_i32 m0, s34, 0x2000
	s_add_u32 s44, s6, 0x80000
	v_lshl_add_u64 v[214:215], s[6:7], 0, v[182:183]
	s_addc_u32 s45, s7, 0
	s_add_i32 s34, s35, s91
	global_load_lds_dwordx4 v[214:215], off
	v_lshl_add_u64 v[216:217], s[44:45], 0, v[0:1]
	s_mov_b32 m0, s34
	v_lshl_add_u64 v[218:219], s[42:43], 0, v[180:181]
	global_load_lds_dwordx4 v[216:217], off
	s_add_i32 m0, s34, 0x2000
	v_lshl_add_u64 v[216:217], s[44:45], 0, v[182:183]
	global_load_lds_dwordx4 v[216:217], off
	s_mov_b32 m0, s93
	v_lshl_add_u64 v[216:217], s[42:43], 0, v[178:179]
	global_load_lds_dwordx4 v[216:217], off
	s_mov_b32 m0, s83
	s_nop 0
	global_load_lds_dwordx4 v[218:219], off
	s_setprio 1
	s_waitcnt lgkmcnt(0)
	s_barrier
	v_mfma_f32_16x16x32_bf16 v[54:57], v[130:133], v[162:165], 0
	v_mfma_f32_16x16x32_bf16 v[46:49], v[138:141], v[162:165], 0
	v_mfma_f32_16x16x32_bf16 v[38:41], v[130:133], v[170:173], 0
	v_mfma_f32_16x16x32_bf16 v[50:53], v[138:141], v[170:173], 0
	v_mfma_f32_16x16x32_bf16 v[18:21], v[130:133], v[190:193], 0
	v_mfma_f32_16x16x32_bf16 v[34:37], v[138:141], v[190:193], 0
	v_mfma_f32_16x16x32_bf16 v[22:25], v[130:133], v[206:209], 0
	v_mfma_f32_16x16x32_bf16 v[74:77], v[138:141], v[206:209], 0
	v_mfma_f32_16x16x32_bf16 v[54:57], v[134:137], v[166:169], v[54:57]
	v_mfma_f32_16x16x32_bf16 v[46:49], v[142:145], v[166:169], v[46:49]
	v_mfma_f32_16x16x32_bf16 v[38:41], v[134:137], v[174:177], v[38:41]
	v_mfma_f32_16x16x32_bf16 v[50:53], v[142:145], v[174:177], v[50:53]
	v_mfma_f32_16x16x32_bf16 v[18:21], v[134:137], v[202:205], v[18:21]
	v_mfma_f32_16x16x32_bf16 v[34:37], v[142:145], v[202:205], v[34:37]
	v_mfma_f32_16x16x32_bf16 v[22:25], v[134:137], v[210:213], v[22:25]
	v_mfma_f32_16x16x32_bf16 v[74:77], v[142:145], v[210:213], v[74:77]
	v_mfma_f32_16x16x32_bf16 v[58:61], v[146:149], v[162:165], 0
	v_mfma_f32_16x16x32_bf16 v[30:33], v[154:157], v[162:165], 0
	v_mfma_f32_16x16x32_bf16 v[42:45], v[146:149], v[170:173], 0
	v_mfma_f32_16x16x32_bf16 v[6:9], v[154:157], v[170:173], 0
	v_mfma_f32_16x16x32_bf16 v[26:29], v[146:149], v[190:193], 0
	v_mfma_f32_16x16x32_bf16 v[10:13], v[154:157], v[190:193], 0
	v_mfma_f32_16x16x32_bf16 v[14:17], v[146:149], v[206:209], 0
	v_mfma_f32_16x16x32_bf16 v[2:5], v[154:157], v[206:209], 0
	v_mfma_f32_16x16x32_bf16 v[58:61], v[150:153], v[166:169], v[58:61]
	v_mfma_f32_16x16x32_bf16 v[30:33], v[158:161], v[166:169], v[30:33]
	v_mfma_f32_16x16x32_bf16 v[42:45], v[150:153], v[174:177], v[42:45]
	v_mfma_f32_16x16x32_bf16 v[6:9], v[158:161], v[174:177], v[6:9]
	v_mfma_f32_16x16x32_bf16 v[26:29], v[150:153], v[202:205], v[26:29]
	v_mfma_f32_16x16x32_bf16 v[10:13], v[158:161], v[202:205], v[10:13]
	v_mfma_f32_16x16x32_bf16 v[14:17], v[150:153], v[210:213], v[14:17]
	v_mfma_f32_16x16x32_bf16 v[2:5], v[158:161], v[210:213], v[2:5]
	s_barrier
	s_setprio 0
	s_add_i32 s34, 0, 0x18000
	s_add_i32 s35, 0, 0x1c000
	v_add_u32_e32 v142, s34, v196
	v_add_u32_e32 v158, s35, v196
	ds_read_b128 v[130:133], v142
	ds_read_b128 v[134:137], v142 offset:1024
	ds_read_b128 v[138:141], v142 offset:2048
	ds_read_b128 v[142:145], v142 offset:3072
	ds_read_b128 v[146:149], v158
	ds_read_b128 v[150:153], v158 offset:1024
	ds_read_b128 v[154:157], v158 offset:2048
	ds_read_b128 v[158:161], v158 offset:3072
	s_add_u32 s42, s42, 0x4000
	s_addc_u32 s43, s43, 0
	s_mov_b32 m0, s79
	v_lshl_add_u64 v[220:221], s[42:43], 0, v[178:179]
	ds_read_b128 v[162:165], v201 offset:32768
	ds_read_b128 v[166:169], v201 offset:33792
	ds_read_b128 v[170:173], v201 offset:34816
	ds_read_b128 v[174:177], v201 offset:35840
	ds_read_b128 v[190:193], v201 offset:36864
	ds_read_b128 v[202:205], v201 offset:37888
	ds_read_b128 v[206:209], v201 offset:38912
	ds_read_b128 v[210:213], v201 offset:39936
	global_load_lds_dwordx4 v[220:221], off
	s_mov_b32 m0, s87
	v_lshl_add_u64 v[220:221], s[42:43], 0, v[180:181]
	global_load_lds_dwordx4 v[220:221], off
	s_setprio 1
	s_waitcnt vmcnt(8) lgkmcnt(0)
	s_barrier
	v_mfma_f32_16x16x32_bf16 v[126:129], v[130:133], v[162:165], v[126:129]
	v_mfma_f32_16x16x32_bf16 v[122:125], v[138:141], v[162:165], v[122:125]
	v_mfma_f32_16x16x32_bf16 v[118:121], v[130:133], v[170:173], v[118:121]
	v_mfma_f32_16x16x32_bf16 v[114:117], v[138:141], v[170:173], v[114:117]
	v_mfma_f32_16x16x32_bf16 v[110:113], v[130:133], v[190:193], v[110:113]
	v_mfma_f32_16x16x32_bf16 v[102:105], v[138:141], v[190:193], v[102:105]
	v_mfma_f32_16x16x32_bf16 v[90:93], v[130:133], v[206:209], v[90:93]
	v_mfma_f32_16x16x32_bf16 v[82:85], v[138:141], v[206:209], v[82:85]
	v_mfma_f32_16x16x32_bf16 v[126:129], v[134:137], v[166:169], v[126:129]
	v_mfma_f32_16x16x32_bf16 v[122:125], v[142:145], v[166:169], v[122:125]
	v_mfma_f32_16x16x32_bf16 v[118:121], v[134:137], v[174:177], v[118:121]
	v_mfma_f32_16x16x32_bf16 v[114:117], v[142:145], v[174:177], v[114:117]
	v_mfma_f32_16x16x32_bf16 v[110:113], v[134:137], v[202:205], v[110:113]
	v_mfma_f32_16x16x32_bf16 v[102:105], v[142:145], v[202:205], v[102:105]
	v_mfma_f32_16x16x32_bf16 v[90:93], v[134:137], v[210:213], v[90:93]
	v_mfma_f32_16x16x32_bf16 v[82:85], v[142:145], v[210:213], v[82:85]
	v_mfma_f32_16x16x32_bf16 v[106:109], v[146:149], v[162:165], v[106:109]
	v_mfma_f32_16x16x32_bf16 v[98:101], v[154:157], v[162:165], v[98:101]
	v_mfma_f32_16x16x32_bf16 v[94:97], v[146:149], v[170:173], v[94:97]
	v_mfma_f32_16x16x32_bf16 v[86:89], v[154:157], v[170:173], v[86:89]
	v_mfma_f32_16x16x32_bf16 v[70:73], v[146:149], v[190:193], v[70:73]
	v_mfma_f32_16x16x32_bf16 v[62:65], v[154:157], v[190:193], v[62:65]
	v_mfma_f32_16x16x32_bf16 v[78:81], v[146:149], v[206:209], v[78:81]
	v_mfma_f32_16x16x32_bf16 v[66:69], v[154:157], v[206:209], v[66:69]
	v_mfma_f32_16x16x32_bf16 v[106:109], v[150:153], v[166:169], v[106:109]
	v_mfma_f32_16x16x32_bf16 v[98:101], v[158:161], v[166:169], v[98:101]
	v_mfma_f32_16x16x32_bf16 v[94:97], v[150:153], v[174:177], v[94:97]
	v_mfma_f32_16x16x32_bf16 v[86:89], v[158:161], v[174:177], v[86:89]
	v_mfma_f32_16x16x32_bf16 v[70:73], v[150:153], v[202:205], v[70:73]
	v_mfma_f32_16x16x32_bf16 v[62:65], v[158:161], v[202:205], v[62:65]
	v_mfma_f32_16x16x32_bf16 v[78:81], v[150:153], v[210:213], v[78:81]
	v_mfma_f32_16x16x32_bf16 v[66:69], v[158:161], v[210:213], v[66:69]
	s_barrier
; #define PG8_STAGE(bufoff, gbase, voff) do { _Pragma("unroll") for (int _i = 0; _i < 2; ++_i) \
;         __builtin_amdgcn_global_load_lds((const unsigned*)((const char*)(gbase) + (voff)[_i]), (LAS unsigned*)(lds + (bufoff) + ldsw + _i * 8192), 16, 0, 0); } while (0)
; #define PG8_LDA(dst, b, h) do { _Pragma("unroll") for (int m = 0; m < 4; ++m) _Pragma("unroll") for (int k = 0; k < 2; ++k) dst[m][k] = *(const LAS bf16x8*)(lds + PG8_SA(b, h) + aoff + m * 2048 + k * 1024); } while (0)
; #define PG8_LDB(dst, b, h) do { _Pragma("unroll") for (int n = 0; n < 2; ++n) _Pragma("unroll") for (int k = 0; k < 2; ++k) dst[n][k] = *(const LAS bf16x8*)(lds + PG8_SB(b, h) + boff + n * 2048 + k * 1024); } while (0)
; #define PG8_WAIT_V(n) asm volatile("s_waitcnt vmcnt(" #n ")" ::: "memory")
; #define PG8_WAIT_L(n) asm volatile("s_waitcnt lgkmcnt(" #n ")" ::: "memory")
; template <class Epi, int AMODE>
; __device__ __forceinline__ void gemm_phase(LAS unsigned char* lds, const Gemm g, const StaticOrder& S, const Epi& E, int stagger_us, int tid_in) {
;     ...
;             const bool last = (t == nt - 2);
;             const char* a1 = cA + (size_t)(t + 1) * kstep;
;             const char* a2 = last ? nA : cA + (size_t)(t + 2) * kstep; const char* b2 = last ? nB : cB + (size_t)(t + 2) * kstep;
;             const char* a3 = a2 + kstep; const char* b3 = b2 + kstep;
;             PG8_LDB(B0, 0, 0); PG8_LDB(B1, 0, 1); PG8_SCHED; PG8_LDA(At, 0, 0); PG8_STAGE(PG8_SA(1, 1), a1 + hstepA, voffA);
;             PG8_WAIT_V(8); PG8_WAIT_L(0); PG8_BAR; PG8_MMA(0, 0, At, B0); PG8_MMA(0, 1, At, B1); PG8_BAR; PG8_SCHED;
;             PG8_LDA(At, 0, 1); PG8_STAGE(PG8_SB(0, 0), b2, voffB); PG8_STAGE(PG8_SB(0, 1), b2 + hstepB, voffB); PG8_STAGE(PG8_SA(0, 0), a2, voffA);
;             PG8_WAIT_V(8); PG8_WAIT_L(0); PG8_BAR; PG8_MMA(1, 0, At, B0); PG8_MMA(1, 1, At, B1); PG8_BAR; PG8_SCHED;
;             PG8_LDB(B0, 1, 0); PG8_LDB(B1, 1, 1); PG8_SCHED; PG8_LDA(At, 1, 0); PG8_STAGE(PG8_SA(0, 1), a2 + hstepA, voffA);
;             PG8_WAIT_V(8); PG8_WAIT_L(0); PG8_BAR; PG8_MMA(0, 0, At, B0); PG8_MMA(0, 1, At, B1); PG8_BAR; PG8_SCHED;
;             PG8_LDA(At, 1, 1); PG8_STAGE(PG8_SB(1, 0), b3, voffB); PG8_STAGE(PG8_SB(1, 1), b3 + hstepB, voffB); PG8_STAGE(PG8_SA(1, 0), a3, voffA);
;             PG8_WAIT_V(8); PG8_WAIT_L(0); PG8_BAR; PG8_MMA(1, 0, At, B0); PG8_MMA(1, 1, At, B1); PG8_BAR; PG8_SCHED;
	s_setprio 0
	s_add_i32 s34, s34, s91
	v_lshl_add_u64 v[194:195], v[194:195], 0, s[74:75]
	s_mov_b32 m0, s34
	ds_read_b128 v[162:165], v201 offset:49152
	ds_read_b128 v[166:169], v201 offset:50176
	ds_read_b128 v[170:173], v201 offset:51200
	ds_read_b128 v[174:177], v201 offset:52224
	ds_read_b128 v[190:193], v201 offset:53248
	ds_read_b128 v[202:205], v201 offset:54272
	ds_read_b128 v[206:209], v201 offset:55296
	ds_read_b128 v[210:213], v201 offset:56320
	global_load_lds_dwordx4 v[194:195], off
	s_add_i32 m0, s34, 0x2000
	s_add_u32 s6, s6, 0x80080
	v_lshl_add_u64 v[194:195], v[214:215], 0, s[74:75]
	s_addc_u32 s7, s7, 0
	s_add_i32 s34, s35, s91
	global_load_lds_dwordx4 v[194:195], off
	s_mov_b32 m0, s34
	v_lshl_add_u64 v[194:195], s[6:7], 0, v[0:1]
	global_load_lds_dwordx4 v[194:195], off
	s_add_i32 m0, s34, 0x2000
	v_lshl_add_u64 v[194:195], s[6:7], 0, v[182:183]
	global_load_lds_dwordx4 v[194:195], off
	s_mov_b32 m0, s67
	v_lshl_add_u64 v[194:195], v[216:217], 0, s[74:75]
	global_load_lds_dwordx4 v[194:195], off
	s_mov_b32 m0, s85
	v_lshl_add_u64 v[194:195], v[218:219], 0, s[74:75]
	global_load_lds_dwordx4 v[194:195], off
	s_setprio 1
	s_waitcnt vmcnt(8) lgkmcnt(0)
	s_barrier
	v_mfma_f32_16x16x32_bf16 v[54:57], v[130:133], v[162:165], v[54:57]
	v_mfma_f32_16x16x32_bf16 v[46:49], v[138:141], v[162:165], v[46:49]
	v_mfma_f32_16x16x32_bf16 v[38:41], v[130:133], v[170:173], v[38:41]
	v_mfma_f32_16x16x32_bf16 v[50:53], v[138:141], v[170:173], v[50:53]
	v_mfma_f32_16x16x32_bf16 v[18:21], v[130:133], v[190:193], v[18:21]
	v_mfma_f32_16x16x32_bf16 v[34:37], v[138:141], v[190:193], v[34:37]
	v_mfma_f32_16x16x32_bf16 v[22:25], v[130:133], v[206:209], v[22:25]
	v_mfma_f32_16x16x32_bf16 v[74:77], v[138:141], v[206:209], v[74:77]
	v_mfma_f32_16x16x32_bf16 v[54:57], v[134:137], v[166:169], v[54:57]
	v_mfma_f32_16x16x32_bf16 v[46:49], v[142:145], v[166:169], v[46:49]
	v_mfma_f32_16x16x32_bf16 v[38:41], v[134:137], v[174:177], v[38:41]
	v_mfma_f32_16x16x32_bf16 v[50:53], v[142:145], v[174:177], v[50:53]
	v_mfma_f32_16x16x32_bf16 v[18:21], v[134:137], v[202:205], v[18:21]
	v_mfma_f32_16x16x32_bf16 v[34:37], v[142:145], v[202:205], v[34:37]
	v_mfma_f32_16x16x32_bf16 v[22:25], v[134:137], v[210:213], v[22:25]
	v_mfma_f32_16x16x32_bf16 v[74:77], v[142:145], v[210:213], v[74:77]
	v_mfma_f32_16x16x32_bf16 v[58:61], v[146:149], v[162:165], v[58:61]
	v_mfma_f32_16x16x32_bf16 v[30:33], v[154:157], v[162:165], v[30:33]
	v_mfma_f32_16x16x32_bf16 v[42:45], v[146:149], v[170:173], v[42:45]
	v_mfma_f32_16x16x32_bf16 v[6:9], v[154:157], v[170:173], v[6:9]
	v_mfma_f32_16x16x32_bf16 v[26:29], v[146:149], v[190:193], v[26:29]
	v_mfma_f32_16x16x32_bf16 v[10:13], v[154:157], v[190:193], v[10:13]
	v_mfma_f32_16x16x32_bf16 v[14:17], v[146:149], v[206:209], v[14:17]
	v_mfma_f32_16x16x32_bf16 v[2:5], v[154:157], v[206:209], v[2:5]
	v_mfma_f32_16x16x32_bf16 v[58:61], v[150:153], v[166:169], v[58:61]
	v_mfma_f32_16x16x32_bf16 v[30:33], v[158:161], v[166:169], v[30:33]
	v_mfma_f32_16x16x32_bf16 v[42:45], v[150:153], v[174:177], v[42:45]
	v_mfma_f32_16x16x32_bf16 v[6:9], v[158:161], v[174:177], v[6:9]
	v_mfma_f32_16x16x32_bf16 v[26:29], v[150:153], v[202:205], v[26:29]
	v_mfma_f32_16x16x32_bf16 v[10:13], v[158:161], v[202:205], v[10:13]
	v_mfma_f32_16x16x32_bf16 v[14:17], v[150:153], v[210:213], v[14:17]
	v_mfma_f32_16x16x32_bf16 v[2:5], v[158:161], v[210:213], v[2:5]
	s_barrier
	s_setprio 0
	s_add_i32 s31, s31, 2
	s_add_u32 s29, s29, 0x100
	s_addc_u32 s30, s30, 0
	s_cmp_gt_u32 s31, 29
	s_mov_b64 s[44:45], s[4:5]
.LBB0_1299:
	s_add_u32 s4, s44, 0x100
	s_addc_u32 s5, s45, 0
	s_add_i32 s34, 0, 0x10000
	s_cmp_eq_u32 s31, 28
	s_cselect_b32 s43, s95, s5
	s_cselect_b32 s42, s94, s4
	s_cselect_b32 s7, s27, s30
	s_cselect_b32 s6, s28, s29
	s_add_i32 s35, 0, 0x14000
	v_add_u32_e32 v142, s34, v196
	v_add_u32_e32 v158, s35, v196
	ds_read_b128 v[130:133], v142
	ds_read_b128 v[134:137], v142 offset:1024
	ds_read_b128 v[138:141], v142 offset:2048
	ds_read_b128 v[142:145], v142 offset:3072
	ds_read_b128 v[146:149], v158
	ds_read_b128 v[150:153], v158 offset:1024
	ds_read_b128 v[154:157], v158 offset:2048
	ds_read_b128 v[158:161], v158 offset:3072
	v_lshl_add_u64 v[194:195], s[44:45], 0, v[186:187]
	s_add_i32 m0, s93, 0xc000
	ds_read_b128 v[162:165], v201
	ds_read_b128 v[166:169], v201 offset:1024
	ds_read_b128 v[170:173], v201 offset:2048
	ds_read_b128 v[174:177], v201 offset:3072
	ds_read_b128 v[190:193], v201 offset:4096
	ds_read_b128 v[202:205], v201 offset:5120
	ds_read_b128 v[206:209], v201 offset:6144
	ds_read_b128 v[210:213], v201 offset:7168
	global_load_lds_dwordx4 v[194:195], off
	s_add_i32 m0, s93, 0xe000
	v_lshl_add_u64 v[194:195], s[44:45], 0, v[188:189]
	global_load_lds_dwordx4 v[194:195], off
	s_setprio 1
	s_waitcnt vmcnt(8) lgkmcnt(0)
	s_barrier
; #define PG8_STAGE(bufoff, gbase, voff) do { _Pragma("unroll") for (int _i = 0; _i < 2; ++_i) \
;         __builtin_amdgcn_global_load_lds((const unsigned*)((const char*)(gbase) + (voff)[_i]), (LAS unsigned*)(lds + (bufoff) + ldsw + _i * 8192), 16, 0, 0); } while (0)
; #define PG8_LDA(dst, b, h) do { _Pragma("unroll") for (int m = 0; m < 4; ++m) _Pragma("unroll") for (int k = 0; k < 2; ++k) dst[m][k] = *(const LAS bf16x8*)(lds + PG8_SA(b, h) + aoff + m * 2048 + k * 1024); } while (0)
; #define PG8_MMA(ai, bj, At, Bt) do { __builtin_amdgcn_s_setprio(1); _Pragma("unroll") for (int m = 0; m < 4; ++m) _Pragma("unroll") for (int n = 0; n < 2; ++n) _Pragma("unroll") for (int k = 0; k < 2; ++k) \
;         acc[ai][bj][m][n] = __builtin_amdgcn_mfma_f32_16x16x32_bf16(Bt[n][k], At[m][k], acc[ai][bj][m][n], 0, 0, 0); __builtin_amdgcn_s_setprio(0); } while (0)
; #define PG8_WAIT_V(n) asm volatile("s_waitcnt vmcnt(" #n ")" ::: "memory")
; #define PG8_WAIT_L(n) asm volatile("s_waitcnt lgkmcnt(" #n ")" ::: "memory")
; #define PG8_BAR __builtin_amdgcn_s_barrier()
; #define PG8_SCHED __builtin_amdgcn_sched_barrier(0)
; template <class Epi, int AMODE>
; __device__ __forceinline__ void gemm_phase(LAS unsigned char* lds, const Gemm g, const StaticOrder& S, const Epi& E, int stagger_us, int tid_in) {
;     ...
;             PG8_WAIT_V(8); PG8_WAIT_L(0); PG8_BAR; PG8_MMA(0, 0, At, B0); PG8_MMA(0, 1, At, B1); PG8_BAR; PG8_SCHED;
;             PG8_LDA(At, 0, 1); PG8_STAGE(PG8_SB(0, 0), b2, voffB); PG8_STAGE(PG8_SB(0, 1), b2 + hstepB, voffB); PG8_STAGE(PG8_SA(0, 0), a2, voffA);
;             PG8_WAIT_V(8); PG8_WAIT_L(0); PG8_BAR; PG8_MMA(1, 0, At, B0); PG8_MMA(1, 1, At, B1); PG8_BAR; PG8_SCHED;
	v_mfma_f32_16x16x32_bf16 v[126:129], v[130:133], v[162:165], v[126:129]
	v_mfma_f32_16x16x32_bf16 v[122:125], v[138:141], v[162:165], v[122:125]
	v_mfma_f32_16x16x32_bf16 v[118:121], v[130:133], v[170:173], v[118:121]
	v_mfma_f32_16x16x32_bf16 v[114:117], v[138:141], v[170:173], v[114:117]
	v_mfma_f32_16x16x32_bf16 v[110:113], v[130:133], v[190:193], v[110:113]
	v_mfma_f32_16x16x32_bf16 v[102:105], v[138:141], v[190:193], v[102:105]
	v_mfma_f32_16x16x32_bf16 v[90:93], v[130:133], v[206:209], v[90:93]
	v_mfma_f32_16x16x32_bf16 v[82:85], v[138:141], v[206:209], v[82:85]
	v_mfma_f32_16x16x32_bf16 v[126:129], v[134:137], v[166:169], v[126:129]
	v_mfma_f32_16x16x32_bf16 v[122:125], v[142:145], v[166:169], v[122:125]
	v_mfma_f32_16x16x32_bf16 v[118:121], v[134:137], v[174:177], v[118:121]
	v_mfma_f32_16x16x32_bf16 v[114:117], v[142:145], v[174:177], v[114:117]
	v_mfma_f32_16x16x32_bf16 v[110:113], v[134:137], v[202:205], v[110:113]
	v_mfma_f32_16x16x32_bf16 v[102:105], v[142:145], v[202:205], v[102:105]
	v_mfma_f32_16x16x32_bf16 v[90:93], v[134:137], v[210:213], v[90:93]
	v_mfma_f32_16x16x32_bf16 v[82:85], v[142:145], v[210:213], v[82:85]
	v_mfma_f32_16x16x32_bf16 v[106:109], v[146:149], v[162:165], v[106:109]
	v_mfma_f32_16x16x32_bf16 v[98:101], v[154:157], v[162:165], v[98:101]
	v_mfma_f32_16x16x32_bf16 v[94:97], v[146:149], v[170:173], v[94:97]
	v_mfma_f32_16x16x32_bf16 v[86:89], v[154:157], v[170:173], v[86:89]
	v_mfma_f32_16x16x32_bf16 v[70:73], v[146:149], v[190:193], v[70:73]
	v_mfma_f32_16x16x32_bf16 v[62:65], v[154:157], v[190:193], v[62:65]
	v_mfma_f32_16x16x32_bf16 v[78:81], v[146:149], v[206:209], v[78:81]
	v_mfma_f32_16x16x32_bf16 v[66:69], v[154:157], v[206:209], v[66:69]
	v_mfma_f32_16x16x32_bf16 v[106:109], v[150:153], v[166:169], v[106:109]
	v_mfma_f32_16x16x32_bf16 v[98:101], v[158:161], v[166:169], v[98:101]
	v_mfma_f32_16x16x32_bf16 v[94:97], v[150:153], v[174:177], v[94:97]
	v_mfma_f32_16x16x32_bf16 v[86:89], v[158:161], v[174:177], v[86:89]
	v_mfma_f32_16x16x32_bf16 v[70:73], v[150:153], v[202:205], v[70:73]
	v_mfma_f32_16x16x32_bf16 v[62:65], v[158:161], v[202:205], v[62:65]
	v_mfma_f32_16x16x32_bf16 v[78:81], v[150:153], v[210:213], v[78:81]
	v_mfma_f32_16x16x32_bf16 v[66:69], v[158:161], v[210:213], v[66:69]
	s_barrier
	s_setprio 0
	s_add_i32 s34, s34, s91
	v_lshl_add_u64 v[194:195], s[6:7], 0, v[0:1]
	s_mov_b32 m0, s34
	ds_read_b128 v[162:165], v201 offset:16384
	ds_read_b128 v[166:169], v201 offset:17408
	ds_read_b128 v[170:173], v201 offset:18432
	ds_read_b128 v[174:177], v201 offset:19456
	ds_read_b128 v[190:193], v201 offset:20480
	ds_read_b128 v[202:205], v201 offset:21504
	ds_read_b128 v[206:209], v201 offset:22528
	ds_read_b128 v[210:213], v201 offset:23552
	global_load_lds_dwordx4 v[194:195], off
	s_add_i32 m0, s34, 0x2000
	s_add_u32 s44, s6, 0x80000
	v_lshl_add_u64 v[214:215], s[6:7], 0, v[182:183]
	s_addc_u32 s45, s7, 0
	s_add_i32 s34, s35, s91
	global_load_lds_dwordx4 v[214:215], off
	v_lshl_add_u64 v[216:217], s[44:45], 0, v[0:1]
	s_mov_b32 m0, s34
	v_lshl_add_u64 v[218:219], s[42:43], 0, v[180:181]
	global_load_lds_dwordx4 v[216:217], off
	s_add_i32 m0, s34, 0x2000
	v_lshl_add_u64 v[216:217], s[44:45], 0, v[182:183]
	global_load_lds_dwordx4 v[216:217], off
	s_mov_b32 m0, s93
	v_lshl_add_u64 v[216:217], s[42:43], 0, v[178:179]
	global_load_lds_dwordx4 v[216:217], off
	s_mov_b32 m0, s83
	s_nop 0
	global_load_lds_dwordx4 v[218:219], off
	s_setprio 1
	s_waitcnt vmcnt(8) lgkmcnt(0)
	s_barrier
	v_mfma_f32_16x16x32_bf16 v[54:57], v[130:133], v[162:165], v[54:57]
	v_mfma_f32_16x16x32_bf16 v[46:49], v[138:141], v[162:165], v[46:49]
	v_mfma_f32_16x16x32_bf16 v[38:41], v[130:133], v[170:173], v[38:41]
	v_mfma_f32_16x16x32_bf16 v[50:53], v[138:141], v[170:173], v[50:53]
	v_mfma_f32_16x16x32_bf16 v[18:21], v[130:133], v[190:193], v[18:21]
	v_mfma_f32_16x16x32_bf16 v[34:37], v[138:141], v[190:193], v[34:37]
	v_mfma_f32_16x16x32_bf16 v[22:25], v[130:133], v[206:209], v[22:25]
	v_mfma_f32_16x16x32_bf16 v[74:77], v[138:141], v[206:209], v[74:77]
	v_mfma_f32_16x16x32_bf16 v[54:57], v[134:137], v[166:169], v[54:57]
	v_mfma_f32_16x16x32_bf16 v[46:49], v[142:145], v[166:169], v[46:49]
	v_mfma_f32_16x16x32_bf16 v[38:41], v[134:137], v[174:177], v[38:41]
	v_mfma_f32_16x16x32_bf16 v[50:53], v[142:145], v[174:177], v[50:53]
	v_mfma_f32_16x16x32_bf16 v[18:21], v[134:137], v[202:205], v[18:21]
	v_mfma_f32_16x16x32_bf16 v[34:37], v[142:145], v[202:205], v[34:37]
	v_mfma_f32_16x16x32_bf16 v[22:25], v[134:137], v[210:213], v[22:25]
	v_mfma_f32_16x16x32_bf16 v[74:77], v[142:145], v[210:213], v[74:77]
	v_mfma_f32_16x16x32_bf16 v[58:61], v[146:149], v[162:165], v[58:61]
	v_mfma_f32_16x16x32_bf16 v[30:33], v[154:157], v[162:165], v[30:33]
	v_mfma_f32_16x16x32_bf16 v[42:45], v[146:149], v[170:173], v[42:45]
	v_mfma_f32_16x16x32_bf16 v[6:9], v[154:157], v[170:173], v[6:9]
	v_mfma_f32_16x16x32_bf16 v[26:29], v[146:149], v[190:193], v[26:29]
	v_mfma_f32_16x16x32_bf16 v[10:13], v[154:157], v[190:193], v[10:13]
	v_mfma_f32_16x16x32_bf16 v[14:17], v[146:149], v[206:209], v[14:17]
	v_mfma_f32_16x16x32_bf16 v[2:5], v[154:157], v[206:209], v[2:5]
	v_mfma_f32_16x16x32_bf16 v[58:61], v[150:153], v[166:169], v[58:61]
	v_mfma_f32_16x16x32_bf16 v[30:33], v[158:161], v[166:169], v[30:33]
	v_mfma_f32_16x16x32_bf16 v[42:45], v[150:153], v[174:177], v[42:45]
	v_mfma_f32_16x16x32_bf16 v[6:9], v[158:161], v[174:177], v[6:9]
	v_mfma_f32_16x16x32_bf16 v[26:29], v[150:153], v[202:205], v[26:29]
	v_mfma_f32_16x16x32_bf16 v[10:13], v[158:161], v[202:205], v[10:13]
	v_mfma_f32_16x16x32_bf16 v[14:17], v[150:153], v[210:213], v[14:17]
	v_mfma_f32_16x16x32_bf16 v[2:5], v[158:161], v[210:213], v[2:5]
	s_barrier
; #define PG8_STAGE(bufoff, gbase, voff) do { _Pragma("unroll") for (int _i = 0; _i < 2; ++_i) \
;         __builtin_amdgcn_global_load_lds((const unsigned*)((const char*)(gbase) + (voff)[_i]), (LAS unsigned*)(lds + (bufoff) + ldsw + _i * 8192), 16, 0, 0); } while (0)
; #define PG8_LDA(dst, b, h) do { _Pragma("unroll") for (int m = 0; m < 4; ++m) _Pragma("unroll") for (int k = 0; k < 2; ++k) dst[m][k] = *(const LAS bf16x8*)(lds + PG8_SA(b, h) + aoff + m * 2048 + k * 1024); } while (0)
; #define PG8_LDB(dst, b, h) do { _Pragma("unroll") for (int n = 0; n < 2; ++n) _Pragma("unroll") for (int k = 0; k < 2; ++k) dst[n][k] = *(const LAS bf16x8*)(lds + PG8_SB(b, h) + boff + n * 2048 + k * 1024); } while (0)
; #define PG8_MMA(ai, bj, At, Bt) do { __builtin_amdgcn_s_setprio(1); _Pragma("unroll") for (int m = 0; m < 4; ++m) _Pragma("unroll") for (int n = 0; n < 2; ++n) _Pragma("unroll") for (int k = 0; k < 2; ++k) \
;         acc[ai][bj][m][n] = __builtin_amdgcn_mfma_f32_16x16x32_bf16(Bt[n][k], At[m][k], acc[ai][bj][m][n], 0, 0, 0); __builtin_amdgcn_s_setprio(0); } while (0)
; #define PG8_WAIT_V(n) asm volatile("s_waitcnt vmcnt(" #n ")" ::: "memory")
; #define PG8_WAIT_L(n) asm volatile("s_waitcnt lgkmcnt(" #n ")" ::: "memory")
; #define PG8_BAR __builtin_amdgcn_s_barrier()
; #define PG8_SCHED __builtin_amdgcn_sched_barrier(0)
; template <class Epi, int AMODE>
; __device__ __forceinline__ void gemm_phase(LAS unsigned char* lds, const Gemm g, const StaticOrder& S, const Epi& E, int stagger_us, int tid_in) {
;     ...
;             PG8_LDB(B0, 1, 0); PG8_LDB(B1, 1, 1); PG8_SCHED; PG8_LDA(At, 1, 0); PG8_STAGE(PG8_SA(0, 1), a2 + hstepA, voffA);
;             PG8_WAIT_V(8); PG8_WAIT_L(0); PG8_BAR; PG8_MMA(0, 0, At, B0); PG8_MMA(0, 1, At, B1); PG8_BAR; PG8_SCHED;
;             PG8_LDA(At, 1, 1); PG8_STAGE(PG8_SB(1, 0), b3, voffB); PG8_STAGE(PG8_SB(1, 1), b3 + hstepB, voffB); PG8_STAGE(PG8_SA(1, 0), a3, voffA);
;             PG8_WAIT_V(8); PG8_WAIT_L(0); PG8_BAR; PG8_MMA(1, 0, At, B0); PG8_MMA(1, 1, At, B1); PG8_BAR; PG8_SCHED;
;         }
;         if (wr == 0) PG8_BAR;
	s_setprio 0
	s_add_i32 s34, 0, 0x18000
	s_add_i32 s35, 0, 0x1c000
	v_add_u32_e32 v142, s34, v196
	v_add_u32_e32 v158, s35, v196
	ds_read_b128 v[130:133], v142
	ds_read_b128 v[134:137], v142 offset:1024
	ds_read_b128 v[138:141], v142 offset:2048
	ds_read_b128 v[142:145], v142 offset:3072
	ds_read_b128 v[146:149], v158
	ds_read_b128 v[150:153], v158 offset:1024
	ds_read_b128 v[154:157], v158 offset:2048
	ds_read_b128 v[158:161], v158 offset:3072
	s_add_u32 s42, s42, 0x4000
	s_addc_u32 s43, s43, 0
	s_mov_b32 m0, s79
	v_lshl_add_u64 v[220:221], s[42:43], 0, v[178:179]
	ds_read_b128 v[162:165], v201 offset:32768
	ds_read_b128 v[166:169], v201 offset:33792
	ds_read_b128 v[170:173], v201 offset:34816
	ds_read_b128 v[174:177], v201 offset:35840
	ds_read_b128 v[190:193], v201 offset:36864
	ds_read_b128 v[202:205], v201 offset:37888
	ds_read_b128 v[206:209], v201 offset:38912
	ds_read_b128 v[210:213], v201 offset:39936
	global_load_lds_dwordx4 v[220:221], off
	s_mov_b32 m0, s87
	v_lshl_add_u64 v[220:221], s[42:43], 0, v[180:181]
	global_load_lds_dwordx4 v[220:221], off
	s_setprio 1
	s_waitcnt vmcnt(8) lgkmcnt(0)
	s_barrier
	v_mfma_f32_16x16x32_bf16 v[126:129], v[130:133], v[162:165], v[126:129]
	v_mfma_f32_16x16x32_bf16 v[122:125], v[138:141], v[162:165], v[122:125]
	v_mfma_f32_16x16x32_bf16 v[118:121], v[130:133], v[170:173], v[118:121]
	v_mfma_f32_16x16x32_bf16 v[114:117], v[138:141], v[170:173], v[114:117]
	v_mfma_f32_16x16x32_bf16 v[110:113], v[130:133], v[190:193], v[110:113]
	v_mfma_f32_16x16x32_bf16 v[102:105], v[138:141], v[190:193], v[102:105]
	v_mfma_f32_16x16x32_bf16 v[90:93], v[130:133], v[206:209], v[90:93]
	v_mfma_f32_16x16x32_bf16 v[82:85], v[138:141], v[206:209], v[82:85]
	v_mfma_f32_16x16x32_bf16 v[126:129], v[134:137], v[166:169], v[126:129]
	v_mfma_f32_16x16x32_bf16 v[122:125], v[142:145], v[166:169], v[122:125]
	v_mfma_f32_16x16x32_bf16 v[118:121], v[134:137], v[174:177], v[118:121]
	v_mfma_f32_16x16x32_bf16 v[114:117], v[142:145], v[174:177], v[114:117]
	v_mfma_f32_16x16x32_bf16 v[110:113], v[134:137], v[202:205], v[110:113]
	v_mfma_f32_16x16x32_bf16 v[102:105], v[142:145], v[202:205], v[102:105]
	v_mfma_f32_16x16x32_bf16 v[90:93], v[134:137], v[210:213], v[90:93]
	v_mfma_f32_16x16x32_bf16 v[82:85], v[142:145], v[210:213], v[82:85]
	v_mfma_f32_16x16x32_bf16 v[106:109], v[146:149], v[162:165], v[106:109]
	v_mfma_f32_16x16x32_bf16 v[98:101], v[154:157], v[162:165], v[98:101]
	v_mfma_f32_16x16x32_bf16 v[94:97], v[146:149], v[170:173], v[94:97]
	v_mfma_f32_16x16x32_bf16 v[86:89], v[154:157], v[170:173], v[86:89]
	v_mfma_f32_16x16x32_bf16 v[70:73], v[146:149], v[190:193], v[70:73]
	v_mfma_f32_16x16x32_bf16 v[62:65], v[154:157], v[190:193], v[62:65]
	v_mfma_f32_16x16x32_bf16 v[78:81], v[146:149], v[206:209], v[78:81]
	v_mfma_f32_16x16x32_bf16 v[66:69], v[154:157], v[206:209], v[66:69]
	v_mfma_f32_16x16x32_bf16 v[106:109], v[150:153], v[166:169], v[106:109]
	v_mfma_f32_16x16x32_bf16 v[98:101], v[158:161], v[166:169], v[98:101]
	v_mfma_f32_16x16x32_bf16 v[94:97], v[150:153], v[174:177], v[94:97]
	v_mfma_f32_16x16x32_bf16 v[86:89], v[158:161], v[174:177], v[86:89]
	v_mfma_f32_16x16x32_bf16 v[70:73], v[150:153], v[202:205], v[70:73]
	v_mfma_f32_16x16x32_bf16 v[62:65], v[158:161], v[202:205], v[62:65]
	v_mfma_f32_16x16x32_bf16 v[78:81], v[150:153], v[210:213], v[78:81]
	v_mfma_f32_16x16x32_bf16 v[66:69], v[158:161], v[210:213], v[66:69]
	s_barrier
	s_setprio 0
	s_add_i32 s34, s34, s91
	v_lshl_add_u64 v[194:195], v[194:195], 0, s[74:75]
	s_mov_b32 m0, s34
	ds_read_b128 v[162:165], v201 offset:49152
	ds_read_b128 v[166:169], v201 offset:50176
	ds_read_b128 v[170:173], v201 offset:51200
	ds_read_b128 v[174:177], v201 offset:52224
	ds_read_b128 v[190:193], v201 offset:53248
	ds_read_b128 v[202:205], v201 offset:54272
	ds_read_b128 v[206:209], v201 offset:55296
	ds_read_b128 v[210:213], v201 offset:56320
	global_load_lds_dwordx4 v[194:195], off
	s_add_i32 m0, s34, 0x2000
	s_add_u32 s6, s6, 0x80080
	v_lshl_add_u64 v[194:195], v[214:215], 0, s[74:75]
	s_addc_u32 s7, s7, 0
	s_add_i32 s34, s35, s91
	global_load_lds_dwordx4 v[194:195], off
	s_mov_b32 m0, s34
	v_lshl_add_u64 v[194:195], s[6:7], 0, v[0:1]
	global_load_lds_dwordx4 v[194:195], off
	s_add_i32 m0, s34, 0x2000
	v_lshl_add_u64 v[194:195], s[6:7], 0, v[182:183]
	global_load_lds_dwordx4 v[194:195], off
	s_mov_b32 m0, s67
	v_lshl_add_u64 v[194:195], v[216:217], 0, s[74:75]
	global_load_lds_dwordx4 v[194:195], off
	s_mov_b32 m0, s85
	v_lshl_add_u64 v[194:195], v[218:219], 0, s[74:75]
	global_load_lds_dwordx4 v[194:195], off
	s_setprio 1
	s_waitcnt vmcnt(8) lgkmcnt(0)
	s_barrier
	v_mfma_f32_16x16x32_bf16 v[54:57], v[130:133], v[162:165], v[54:57]
	v_mfma_f32_16x16x32_bf16 v[46:49], v[138:141], v[162:165], v[46:49]
	v_mfma_f32_16x16x32_bf16 v[38:41], v[130:133], v[170:173], v[38:41]
	v_mfma_f32_16x16x32_bf16 v[50:53], v[138:141], v[170:173], v[50:53]
	v_mfma_f32_16x16x32_bf16 v[18:21], v[130:133], v[190:193], v[18:21]
	v_mfma_f32_16x16x32_bf16 v[34:37], v[138:141], v[190:193], v[34:37]
	v_mfma_f32_16x16x32_bf16 v[22:25], v[130:133], v[206:209], v[22:25]
	v_mfma_f32_16x16x32_bf16 v[74:77], v[138:141], v[206:209], v[74:77]
	v_mfma_f32_16x16x32_bf16 v[54:57], v[134:137], v[166:169], v[54:57]
	v_mfma_f32_16x16x32_bf16 v[46:49], v[142:145], v[166:169], v[46:49]
	v_mfma_f32_16x16x32_bf16 v[38:41], v[134:137], v[174:177], v[38:41]
	v_mfma_f32_16x16x32_bf16 v[50:53], v[142:145], v[174:177], v[50:53]
	v_mfma_f32_16x16x32_bf16 v[18:21], v[134:137], v[202:205], v[18:21]
	v_mfma_f32_16x16x32_bf16 v[34:37], v[142:145], v[202:205], v[34:37]
	v_mfma_f32_16x16x32_bf16 v[22:25], v[134:137], v[210:213], v[22:25]
	v_mfma_f32_16x16x32_bf16 v[74:77], v[142:145], v[210:213], v[74:77]
	v_mfma_f32_16x16x32_bf16 v[58:61], v[146:149], v[162:165], v[58:61]
	v_mfma_f32_16x16x32_bf16 v[30:33], v[154:157], v[162:165], v[30:33]
	v_mfma_f32_16x16x32_bf16 v[42:45], v[146:149], v[170:173], v[42:45]
	v_mfma_f32_16x16x32_bf16 v[6:9], v[154:157], v[170:173], v[6:9]
	v_mfma_f32_16x16x32_bf16 v[26:29], v[146:149], v[190:193], v[26:29]
	v_mfma_f32_16x16x32_bf16 v[10:13], v[154:157], v[190:193], v[10:13]
	v_mfma_f32_16x16x32_bf16 v[14:17], v[146:149], v[206:209], v[14:17]
	v_mfma_f32_16x16x32_bf16 v[2:5], v[154:157], v[206:209], v[2:5]
	v_mfma_f32_16x16x32_bf16 v[58:61], v[150:153], v[166:169], v[58:61]
	v_mfma_f32_16x16x32_bf16 v[30:33], v[158:161], v[166:169], v[30:33]
	v_mfma_f32_16x16x32_bf16 v[42:45], v[150:153], v[174:177], v[42:45]
	v_mfma_f32_16x16x32_bf16 v[6:9], v[158:161], v[174:177], v[6:9]
	v_mfma_f32_16x16x32_bf16 v[26:29], v[150:153], v[202:205], v[26:29]
	v_mfma_f32_16x16x32_bf16 v[10:13], v[158:161], v[202:205], v[10:13]
	v_mfma_f32_16x16x32_bf16 v[14:17], v[150:153], v[210:213], v[14:17]
	v_mfma_f32_16x16x32_bf16 v[2:5], v[158:161], v[210:213], v[2:5]
	s_barrier
	s_setprio 0
	s_add_i32 s31, s31, 2
	s_add_u32 s29, s29, 0x100
	s_addc_u32 s30, s30, 0
	s_cmp_gt_u32 s31, 29
	s_mov_b64 s[44:45], s[4:5]
	s_cbranch_scc0 .LBB0_1299
	s_and_b64 vcc, exec, s[48:49]
	s_cbranch_vccz .LBB0_1302
	s_barrier

; #define PG8_STAGE(bufoff, gbase, voff) do { _Pragma("unroll") for (int _i = 0; _i < 2; ++_i) \
;         __builtin_amdgcn_global_load_lds((const unsigned*)((const char*)(gbase) + (voff)[_i]), (LAS unsigned*)(lds + (bufoff) + ldsw + _i * 8192), 16, 0, 0); } while (0)
; #define PG8_LDA(dst, b, h) do { _Pragma("unroll") for (int m = 0; m < 4; ++m) _Pragma("unroll") for (int k = 0; k < 2; ++k) dst[m][k] = *(const LAS bf16x8*)(lds + PG8_SA(b, h) + aoff + m * 2048 + k * 1024); } while (0)
; #define PG8_LDB(dst, b, h) do { _Pragma("unroll") for (int n = 0; n < 2; ++n) _Pragma("unroll") for (int k = 0; k < 2; ++k) dst[n][k] = *(const LAS bf16x8*)(lds + PG8_SB(b, h) + boff + n * 2048 + k * 1024); } while (0)
; #define PG8_MMA(ai, bj, At, Bt) do { __builtin_amdgcn_s_setprio(1); _Pragma("unroll") for (int m = 0; m < 4; ++m) _Pragma("unroll") for (int n = 0; n < 2; ++n) _Pragma("unroll") for (int k = 0; k < 2; ++k) \
;         acc[ai][bj][m][n] = __builtin_amdgcn_mfma_f32_16x16x32_bf16(Bt[n][k], At[m][k], acc[ai][bj][m][n], 0, 0, 0); __builtin_amdgcn_s_setprio(0); } while (0)
; #define PG8_WAIT_V(n) asm volatile("s_waitcnt vmcnt(" #n ")" ::: "memory")
; #define PG8_WAIT_L(n) asm volatile("s_waitcnt lgkmcnt(" #n ")" ::: "memory")
; #define PG8_BAR __builtin_amdgcn_s_barrier()
; #define PG8_SCHED __builtin_amdgcn_sched_barrier(0)
; template <class Epi, int AMODE>
; __device__ __forceinline__ void gemm_phase(LAS unsigned char* lds, const Gemm g, const StaticOrder& S, const Epi& E, int stagger_us, int tid_in) {
;     ...
;             const bool last = (t == nt - 2);
;             const char* a1 = cA + (size_t)(t + 1) * kstep;
;             const char* a2 = last ? nA : cA + (size_t)(t + 2) * kstep; const char* b2 = last ? nB : cB + (size_t)(t + 2) * kstep;
;             const char* a3 = a2 + kstep; const char* b3 = b2 + kstep;
;             PG8_LDB(B0, 0, 0); PG8_LDB(B1, 0, 1); PG8_SCHED; PG8_LDA(At, 0, 0); PG8_STAGE(PG8_SA(1, 1), a1 + hstepA, voffA);
;             PG8_WAIT_V(8); PG8_WAIT_L(0); PG8_BAR; PG8_MMA(0, 0, At, B0); PG8_MMA(0, 1, At, B1); PG8_BAR; PG8_SCHED;
;             PG8_LDA(At, 0, 1); PG8_STAGE(PG8_SB(0, 0), b2, voffB); PG8_STAGE(PG8_SB(0, 1), b2 + hstepB, voffB); PG8_STAGE(PG8_SA(0, 0), a2, voffA);
.LBB0_1476:
	s_add_u32 s4, s54, 0x100
	s_addc_u32 s5, s55, 0
	s_add_i32 s30, 0, 0x10000
	s_cmpk_eq_i32 s29, 0x52
	s_cselect_b32 s57, s41, s5
	s_cselect_b32 s56, s40, s4
	s_cselect_b32 s7, s53, s28
	s_cselect_b32 s6, s52, s27
	s_add_i32 s34, 0, 0x14000
	v_add_u32_e32 v102, s30, v162
	v_add_u32_e32 v165, s34, v162
	ds_read_b128 v[66:69], v102
	ds_read_b128 v[70:73], v102 offset:1024
	ds_read_b128 v[74:77], v102 offset:2048
	ds_read_b128 v[102:105], v102 offset:3072
	ds_read_b128 v[152:155], v165
	ds_read_b128 v[156:159], v165 offset:1024
	ds_read_b128 v[166:169], v165 offset:2048
	ds_read_b128 v[170:173], v165 offset:3072
	v_lshl_add_u64 v[206:207], s[54:55], 0, v[148:149]
	s_add_i32 m0, s13, 0xc000
	ds_read_b128 v[174:177], v164
	ds_read_b128 v[178:181], v164 offset:1024
	ds_read_b128 v[182:185], v164 offset:2048
	ds_read_b128 v[186:189], v164 offset:3072
	ds_read_b128 v[190:193], v164 offset:4096
	ds_read_b128 v[194:197], v164 offset:5120
	ds_read_b128 v[198:201], v164 offset:6144
	ds_read_b128 v[202:205], v164 offset:7168
	global_load_lds_dwordx4 v[206:207], off
	s_add_i32 m0, s13, 0xe000
	v_lshl_add_u64 v[206:207], s[54:55], 0, v[150:151]
	global_load_lds_dwordx4 v[206:207], off
	s_setprio 1
	s_waitcnt vmcnt(8) lgkmcnt(0)
	s_barrier
	v_mfma_f32_16x16x32_bf16 v[142:145], v[66:69], v[174:177], v[142:145]
	v_mfma_f32_16x16x32_bf16 v[138:141], v[74:77], v[174:177], v[138:141]
	v_mfma_f32_16x16x32_bf16 v[134:137], v[66:69], v[182:185], v[134:137]
	v_mfma_f32_16x16x32_bf16 v[130:133], v[74:77], v[182:185], v[130:133]
	v_mfma_f32_16x16x32_bf16 v[110:113], v[66:69], v[190:193], v[110:113]
	v_mfma_f32_16x16x32_bf16 v[106:109], v[74:77], v[190:193], v[106:109]
	v_mfma_f32_16x16x32_bf16 v[98:101], v[66:69], v[198:201], v[98:101]
	v_mfma_f32_16x16x32_bf16 v[94:97], v[74:77], v[198:201], v[94:97]
	v_mfma_f32_16x16x32_bf16 v[142:145], v[70:73], v[178:181], v[142:145]
	v_mfma_f32_16x16x32_bf16 v[138:141], v[102:105], v[178:181], v[138:141]
	v_mfma_f32_16x16x32_bf16 v[134:137], v[70:73], v[186:189], v[134:137]
	v_mfma_f32_16x16x32_bf16 v[130:133], v[102:105], v[186:189], v[130:133]
	v_mfma_f32_16x16x32_bf16 v[110:113], v[70:73], v[194:197], v[110:113]
	v_mfma_f32_16x16x32_bf16 v[106:109], v[102:105], v[194:197], v[106:109]
	v_mfma_f32_16x16x32_bf16 v[98:101], v[70:73], v[202:205], v[98:101]
	v_mfma_f32_16x16x32_bf16 v[94:97], v[102:105], v[202:205], v[94:97]
	v_mfma_f32_16x16x32_bf16 v[126:129], v[152:155], v[174:177], v[126:129]
	v_mfma_f32_16x16x32_bf16 v[122:125], v[166:169], v[174:177], v[122:125]
	v_mfma_f32_16x16x32_bf16 v[118:121], v[152:155], v[182:185], v[118:121]
	v_mfma_f32_16x16x32_bf16 v[114:117], v[166:169], v[182:185], v[114:117]
	v_mfma_f32_16x16x32_bf16 v[90:93], v[152:155], v[190:193], v[90:93]
	v_mfma_f32_16x16x32_bf16 v[86:89], v[166:169], v[190:193], v[86:89]
	v_mfma_f32_16x16x32_bf16 v[82:85], v[152:155], v[198:201], v[82:85]
	v_mfma_f32_16x16x32_bf16 v[78:81], v[166:169], v[198:201], v[78:81]
	v_mfma_f32_16x16x32_bf16 v[126:129], v[156:159], v[178:181], v[126:129]
	v_mfma_f32_16x16x32_bf16 v[122:125], v[170:173], v[178:181], v[122:125]
	v_mfma_f32_16x16x32_bf16 v[118:121], v[156:159], v[186:189], v[118:121]
	v_mfma_f32_16x16x32_bf16 v[114:117], v[170:173], v[186:189], v[114:117]
	v_mfma_f32_16x16x32_bf16 v[90:93], v[156:159], v[194:197], v[90:93]
	v_mfma_f32_16x16x32_bf16 v[86:89], v[170:173], v[194:197], v[86:89]
	v_mfma_f32_16x16x32_bf16 v[82:85], v[156:159], v[202:205], v[82:85]
	v_mfma_f32_16x16x32_bf16 v[78:81], v[170:173], v[202:205], v[78:81]
	s_barrier
	s_setprio 0
	s_add_i32 s30, s30, s12
	v_lshl_add_u64 v[206:207], s[6:7], 0, v[0:1]
	s_mov_b32 m0, s30
	ds_read_b128 v[174:177], v164 offset:16384
	ds_read_b128 v[178:181], v164 offset:17408
	ds_read_b128 v[182:185], v164 offset:18432
	ds_read_b128 v[186:189], v164 offset:19456
	ds_read_b128 v[190:193], v164 offset:20480
	ds_read_b128 v[194:197], v164 offset:21504
	ds_read_b128 v[198:201], v164 offset:22528
	ds_read_b128 v[202:205], v164 offset:23552
	global_load_lds_dwordx4 v[206:207], off
	s_add_i32 m0, s30, 0x2000
	s_add_u32 s30, s6, 0x158000
	v_lshl_add_u64 v[208:209], s[6:7], 0, v[146:147]
	s_addc_u32 s31, s7, 0
	s_add_i32 s34, s34, s12
	global_load_lds_dwordx4 v[208:209], off
	v_lshl_add_u64 v[210:211], s[30:31], 0, v[0:1]
	s_mov_b32 m0, s34
	v_lshl_add_u64 v[212:213], s[56:57], 0, v[146:147]
	global_load_lds_dwordx4 v[210:211], off
	s_add_i32 m0, s34, 0x2000
	v_lshl_add_u64 v[210:211], s[30:31], 0, v[146:147]
	global_load_lds_dwordx4 v[210:211], off
	s_mov_b32 m0, s13
	v_lshl_add_u64 v[210:211], s[56:57], 0, v[0:1]
	global_load_lds_dwordx4 v[210:211], off
	s_mov_b32 m0, s24
	s_nop 0
	global_load_lds_dwordx4 v[212:213], off
	s_setprio 1
	s_waitcnt vmcnt(8) lgkmcnt(0)
	s_barrier
; #define PG8_STAGE(bufoff, gbase, voff) do { _Pragma("unroll") for (int _i = 0; _i < 2; ++_i) \
;         __builtin_amdgcn_global_load_lds((const unsigned*)((const char*)(gbase) + (voff)[_i]), (LAS unsigned*)(lds + (bufoff) + ldsw + _i * 8192), 16, 0, 0); } while (0)
; #define PG8_LDA(dst, b, h) do { _Pragma("unroll") for (int m = 0; m < 4; ++m) _Pragma("unroll") for (int k = 0; k < 2; ++k) dst[m][k] = *(const LAS bf16x8*)(lds + PG8_SA(b, h) + aoff + m * 2048 + k * 1024); } while (0)
; #define PG8_LDB(dst, b, h) do { _Pragma("unroll") for (int n = 0; n < 2; ++n) _Pragma("unroll") for (int k = 0; k < 2; ++k) dst[n][k] = *(const LAS bf16x8*)(lds + PG8_SB(b, h) + boff + n * 2048 + k * 1024); } while (0)
; #define PG8_MMA(ai, bj, At, Bt) do { __builtin_amdgcn_s_setprio(1); _Pragma("unroll") for (int m = 0; m < 4; ++m) _Pragma("unroll") for (int n = 0; n < 2; ++n) _Pragma("unroll") for (int k = 0; k < 2; ++k) \
;         acc[ai][bj][m][n] = __builtin_amdgcn_mfma_f32_16x16x32_bf16(Bt[n][k], At[m][k], acc[ai][bj][m][n], 0, 0, 0); __builtin_amdgcn_s_setprio(0); } while (0)
; #define PG8_WAIT_V(n) asm volatile("s_waitcnt vmcnt(" #n ")" ::: "memory")
; #define PG8_WAIT_L(n) asm volatile("s_waitcnt lgkmcnt(" #n ")" ::: "memory")
; #define PG8_BAR __builtin_amdgcn_s_barrier()
; #define PG8_SCHED __builtin_amdgcn_sched_barrier(0)
; template <class Epi, int AMODE>
; __device__ __forceinline__ void gemm_phase(LAS unsigned char* lds, const Gemm g, const StaticOrder& S, const Epi& E, int stagger_us, int tid_in) {
;     ...
;             PG8_WAIT_V(8); PG8_WAIT_L(0); PG8_BAR; PG8_MMA(1, 0, At, B0); PG8_MMA(1, 1, At, B1); PG8_BAR; PG8_SCHED;
;             PG8_LDB(B0, 1, 0); PG8_LDB(B1, 1, 1); PG8_SCHED; PG8_LDA(At, 1, 0); PG8_STAGE(PG8_SA(0, 1), a2 + hstepA, voffA);
;             PG8_WAIT_V(8); PG8_WAIT_L(0); PG8_BAR; PG8_MMA(0, 0, At, B0); PG8_MMA(0, 1, At, B1); PG8_BAR; PG8_SCHED;
	v_mfma_f32_16x16x32_bf16 v[62:65], v[66:69], v[174:177], v[62:65]
	v_mfma_f32_16x16x32_bf16 v[58:61], v[74:77], v[174:177], v[58:61]
	v_mfma_f32_16x16x32_bf16 v[54:57], v[66:69], v[182:185], v[54:57]
	v_mfma_f32_16x16x32_bf16 v[50:53], v[74:77], v[182:185], v[50:53]
	v_mfma_f32_16x16x32_bf16 v[30:33], v[66:69], v[190:193], v[30:33]
	v_mfma_f32_16x16x32_bf16 v[26:29], v[74:77], v[190:193], v[26:29]
	v_mfma_f32_16x16x32_bf16 v[22:25], v[66:69], v[198:201], v[22:25]
	v_mfma_f32_16x16x32_bf16 v[10:13], v[74:77], v[198:201], v[10:13]
	v_mfma_f32_16x16x32_bf16 v[62:65], v[70:73], v[178:181], v[62:65]
	v_mfma_f32_16x16x32_bf16 v[58:61], v[102:105], v[178:181], v[58:61]
	v_mfma_f32_16x16x32_bf16 v[54:57], v[70:73], v[186:189], v[54:57]
	v_mfma_f32_16x16x32_bf16 v[50:53], v[102:105], v[186:189], v[50:53]
	v_mfma_f32_16x16x32_bf16 v[30:33], v[70:73], v[194:197], v[30:33]
	v_mfma_f32_16x16x32_bf16 v[26:29], v[102:105], v[194:197], v[26:29]
	v_mfma_f32_16x16x32_bf16 v[22:25], v[70:73], v[202:205], v[22:25]
	v_mfma_f32_16x16x32_bf16 v[10:13], v[102:105], v[202:205], v[10:13]
	v_mfma_f32_16x16x32_bf16 v[46:49], v[152:155], v[174:177], v[46:49]
	v_mfma_f32_16x16x32_bf16 v[42:45], v[166:169], v[174:177], v[42:45]
	v_mfma_f32_16x16x32_bf16 v[38:41], v[152:155], v[182:185], v[38:41]
	v_mfma_f32_16x16x32_bf16 v[34:37], v[166:169], v[182:185], v[34:37]
	v_mfma_f32_16x16x32_bf16 v[18:21], v[152:155], v[190:193], v[18:21]
	v_mfma_f32_16x16x32_bf16 v[14:17], v[166:169], v[190:193], v[14:17]
	v_mfma_f32_16x16x32_bf16 v[6:9], v[152:155], v[198:201], v[6:9]
	v_mfma_f32_16x16x32_bf16 v[2:5], v[166:169], v[198:201], v[2:5]
	v_mfma_f32_16x16x32_bf16 v[46:49], v[156:159], v[178:181], v[46:49]
	v_mfma_f32_16x16x32_bf16 v[42:45], v[170:173], v[178:181], v[42:45]
	v_mfma_f32_16x16x32_bf16 v[38:41], v[156:159], v[186:189], v[38:41]
	v_mfma_f32_16x16x32_bf16 v[34:37], v[170:173], v[186:189], v[34:37]
	v_mfma_f32_16x16x32_bf16 v[18:21], v[156:159], v[194:197], v[18:21]
	v_mfma_f32_16x16x32_bf16 v[14:17], v[170:173], v[194:197], v[14:17]
	v_mfma_f32_16x16x32_bf16 v[6:9], v[156:159], v[202:205], v[6:9]
	v_mfma_f32_16x16x32_bf16 v[2:5], v[170:173], v[202:205], v[2:5]
	s_barrier
	s_setprio 0
	s_add_i32 s34, 0, 0x18000
	s_add_i32 s35, 0, 0x1c000
	v_add_u32_e32 v102, s34, v162
	v_add_u32_e32 v165, s35, v162
	ds_read_b128 v[66:69], v102
	ds_read_b128 v[70:73], v102 offset:1024
	ds_read_b128 v[74:77], v102 offset:2048
	ds_read_b128 v[102:105], v102 offset:3072
	ds_read_b128 v[152:155], v165
	ds_read_b128 v[156:159], v165 offset:1024
	ds_read_b128 v[166:169], v165 offset:2048
	ds_read_b128 v[170:173], v165 offset:3072
	s_add_u32 s30, s56, 0x158000
	s_addc_u32 s31, s57, 0
	s_mov_b32 m0, s25
	v_lshl_add_u64 v[214:215], s[30:31], 0, v[0:1]
	ds_read_b128 v[174:177], v164 offset:32768
	ds_read_b128 v[178:181], v164 offset:33792
	ds_read_b128 v[182:185], v164 offset:34816
	ds_read_b128 v[186:189], v164 offset:35840
	ds_read_b128 v[190:193], v164 offset:36864
	ds_read_b128 v[194:197], v164 offset:37888
	ds_read_b128 v[198:201], v164 offset:38912
	ds_read_b128 v[202:205], v164 offset:39936
	global_load_lds_dwordx4 v[214:215], off
	s_mov_b32 m0, s66
	v_lshl_add_u64 v[214:215], s[30:31], 0, v[146:147]
	global_load_lds_dwordx4 v[214:215], off
	s_setprio 1
	s_waitcnt vmcnt(8) lgkmcnt(0)
	s_barrier
	v_mfma_f32_16x16x32_bf16 v[142:145], v[66:69], v[174:177], v[142:145]
	v_mfma_f32_16x16x32_bf16 v[138:141], v[74:77], v[174:177], v[138:141]
	v_mfma_f32_16x16x32_bf16 v[134:137], v[66:69], v[182:185], v[134:137]
	v_mfma_f32_16x16x32_bf16 v[130:133], v[74:77], v[182:185], v[130:133]
	v_mfma_f32_16x16x32_bf16 v[110:113], v[66:69], v[190:193], v[110:113]
	v_mfma_f32_16x16x32_bf16 v[106:109], v[74:77], v[190:193], v[106:109]
	v_mfma_f32_16x16x32_bf16 v[98:101], v[66:69], v[198:201], v[98:101]
	v_mfma_f32_16x16x32_bf16 v[94:97], v[74:77], v[198:201], v[94:97]
	v_mfma_f32_16x16x32_bf16 v[142:145], v[70:73], v[178:181], v[142:145]
	v_mfma_f32_16x16x32_bf16 v[138:141], v[102:105], v[178:181], v[138:141]
	v_mfma_f32_16x16x32_bf16 v[134:137], v[70:73], v[186:189], v[134:137]
	v_mfma_f32_16x16x32_bf16 v[130:133], v[102:105], v[186:189], v[130:133]
	v_mfma_f32_16x16x32_bf16 v[110:113], v[70:73], v[194:197], v[110:113]
	v_mfma_f32_16x16x32_bf16 v[106:109], v[102:105], v[194:197], v[106:109]
	v_mfma_f32_16x16x32_bf16 v[98:101], v[70:73], v[202:205], v[98:101]
	v_mfma_f32_16x16x32_bf16 v[94:97], v[102:105], v[202:205], v[94:97]
	v_mfma_f32_16x16x32_bf16 v[126:129], v[152:155], v[174:177], v[126:129]
	v_mfma_f32_16x16x32_bf16 v[122:125], v[166:169], v[174:177], v[122:125]
	v_mfma_f32_16x16x32_bf16 v[118:121], v[152:155], v[182:185], v[118:121]
	v_mfma_f32_16x16x32_bf16 v[114:117], v[166:169], v[182:185], v[114:117]
	v_mfma_f32_16x16x32_bf16 v[90:93], v[152:155], v[190:193], v[90:93]
	v_mfma_f32_16x16x32_bf16 v[86:89], v[166:169], v[190:193], v[86:89]
	v_mfma_f32_16x16x32_bf16 v[82:85], v[152:155], v[198:201], v[82:85]
	v_mfma_f32_16x16x32_bf16 v[78:81], v[166:169], v[198:201], v[78:81]
	v_mfma_f32_16x16x32_bf16 v[126:129], v[156:159], v[178:181], v[126:129]
	v_mfma_f32_16x16x32_bf16 v[122:125], v[170:173], v[178:181], v[122:125]
	v_mfma_f32_16x16x32_bf16 v[118:121], v[156:159], v[186:189], v[118:121]
	v_mfma_f32_16x16x32_bf16 v[114:117], v[170:173], v[186:189], v[114:117]
	v_mfma_f32_16x16x32_bf16 v[90:93], v[156:159], v[194:197], v[90:93]
	v_mfma_f32_16x16x32_bf16 v[86:89], v[170:173], v[194:197], v[86:89]
	v_mfma_f32_16x16x32_bf16 v[82:85], v[156:159], v[202:205], v[82:85]
	v_mfma_f32_16x16x32_bf16 v[78:81], v[170:173], v[202:205], v[78:81]
	s_barrier
; #define PG8_STAGE(bufoff, gbase, voff) do { _Pragma("unroll") for (int _i = 0; _i < 2; ++_i) \
;         __builtin_amdgcn_global_load_lds((const unsigned*)((const char*)(gbase) + (voff)[_i]), (LAS unsigned*)(lds + (bufoff) + ldsw + _i * 8192), 16, 0, 0); } while (0)
; #define PG8_LDA(dst, b, h) do { _Pragma("unroll") for (int m = 0; m < 4; ++m) _Pragma("unroll") for (int k = 0; k < 2; ++k) dst[m][k] = *(const LAS bf16x8*)(lds + PG8_SA(b, h) + aoff + m * 2048 + k * 1024); } while (0)
; #define PG8_MMA(ai, bj, At, Bt) do { __builtin_amdgcn_s_setprio(1); _Pragma("unroll") for (int m = 0; m < 4; ++m) _Pragma("unroll") for (int n = 0; n < 2; ++n) _Pragma("unroll") for (int k = 0; k < 2; ++k) \
;         acc[ai][bj][m][n] = __builtin_amdgcn_mfma_f32_16x16x32_bf16(Bt[n][k], At[m][k], acc[ai][bj][m][n], 0, 0, 0); __builtin_amdgcn_s_setprio(0); } while (0)
; #define PG8_WAIT_V(n) asm volatile("s_waitcnt vmcnt(" #n ")" ::: "memory")
; #define PG8_WAIT_L(n) asm volatile("s_waitcnt lgkmcnt(" #n ")" ::: "memory")
; #define PG8_BAR __builtin_amdgcn_s_barrier()
; #define PG8_SCHED __builtin_amdgcn_sched_barrier(0)
; template <class Epi, int AMODE>
; __device__ __forceinline__ void gemm_phase(LAS unsigned char* lds, const Gemm g, const StaticOrder& S, const Epi& E, int stagger_us, int tid_in) {
;     ...
;             PG8_LDA(At, 1, 1); PG8_STAGE(PG8_SB(1, 0), b3, voffB); PG8_STAGE(PG8_SB(1, 1), b3 + hstepB, voffB); PG8_STAGE(PG8_SA(1, 0), a3, voffA);
;             PG8_WAIT_V(8); PG8_WAIT_L(0); PG8_BAR; PG8_MMA(1, 0, At, B0); PG8_MMA(1, 1, At, B1); PG8_BAR; PG8_SCHED;
;         }
;         if (wr == 0) PG8_BAR;
	s_setprio 0
	s_add_i32 s30, s34, s12
	v_lshl_add_u64 v[206:207], v[206:207], 0, s[74:75]
	s_mov_b32 m0, s30
	ds_read_b128 v[174:177], v164 offset:49152
	ds_read_b128 v[178:181], v164 offset:50176
	ds_read_b128 v[182:185], v164 offset:51200
	ds_read_b128 v[186:189], v164 offset:52224
	ds_read_b128 v[190:193], v164 offset:53248
	ds_read_b128 v[194:197], v164 offset:54272
	ds_read_b128 v[198:201], v164 offset:55296
	ds_read_b128 v[202:205], v164 offset:56320
	global_load_lds_dwordx4 v[206:207], off
	s_add_i32 m0, s30, 0x2000
	s_add_u32 s6, s6, 0x158080
	v_lshl_add_u64 v[206:207], v[208:209], 0, s[74:75]
	s_addc_u32 s7, s7, 0
	s_add_i32 s30, s35, s12
	global_load_lds_dwordx4 v[206:207], off
	s_mov_b32 m0, s30
	v_lshl_add_u64 v[206:207], s[6:7], 0, v[0:1]
	global_load_lds_dwordx4 v[206:207], off
	s_add_i32 m0, s30, 0x2000
	v_lshl_add_u64 v[206:207], s[6:7], 0, v[146:147]
	global_load_lds_dwordx4 v[206:207], off
	s_mov_b32 m0, s67
	v_lshl_add_u64 v[206:207], v[210:211], 0, s[74:75]
	global_load_lds_dwordx4 v[206:207], off
	s_mov_b32 m0, s69
	v_lshl_add_u64 v[206:207], v[212:213], 0, s[74:75]
	global_load_lds_dwordx4 v[206:207], off
	s_setprio 1
	s_waitcnt vmcnt(8) lgkmcnt(0)
	s_barrier
	v_mfma_f32_16x16x32_bf16 v[62:65], v[66:69], v[174:177], v[62:65]
	v_mfma_f32_16x16x32_bf16 v[58:61], v[74:77], v[174:177], v[58:61]
	v_mfma_f32_16x16x32_bf16 v[54:57], v[66:69], v[182:185], v[54:57]
	v_mfma_f32_16x16x32_bf16 v[50:53], v[74:77], v[182:185], v[50:53]
	v_mfma_f32_16x16x32_bf16 v[30:33], v[66:69], v[190:193], v[30:33]
	v_mfma_f32_16x16x32_bf16 v[26:29], v[74:77], v[190:193], v[26:29]
	v_mfma_f32_16x16x32_bf16 v[22:25], v[66:69], v[198:201], v[22:25]
	v_mfma_f32_16x16x32_bf16 v[10:13], v[74:77], v[198:201], v[10:13]
	v_mfma_f32_16x16x32_bf16 v[62:65], v[70:73], v[178:181], v[62:65]
	v_mfma_f32_16x16x32_bf16 v[58:61], v[102:105], v[178:181], v[58:61]
	v_mfma_f32_16x16x32_bf16 v[54:57], v[70:73], v[186:189], v[54:57]
	v_mfma_f32_16x16x32_bf16 v[50:53], v[102:105], v[186:189], v[50:53]
	v_mfma_f32_16x16x32_bf16 v[30:33], v[70:73], v[194:197], v[30:33]
	v_mfma_f32_16x16x32_bf16 v[26:29], v[102:105], v[194:197], v[26:29]
	v_mfma_f32_16x16x32_bf16 v[22:25], v[70:73], v[202:205], v[22:25]
	v_mfma_f32_16x16x32_bf16 v[10:13], v[102:105], v[202:205], v[10:13]
	v_mfma_f32_16x16x32_bf16 v[46:49], v[152:155], v[174:177], v[46:49]
	v_mfma_f32_16x16x32_bf16 v[42:45], v[166:169], v[174:177], v[42:45]
	v_mfma_f32_16x16x32_bf16 v[38:41], v[152:155], v[182:185], v[38:41]
	v_mfma_f32_16x16x32_bf16 v[34:37], v[166:169], v[182:185], v[34:37]
	v_mfma_f32_16x16x32_bf16 v[18:21], v[152:155], v[190:193], v[18:21]
	v_mfma_f32_16x16x32_bf16 v[14:17], v[166:169], v[190:193], v[14:17]
	v_mfma_f32_16x16x32_bf16 v[6:9], v[152:155], v[198:201], v[6:9]
	v_mfma_f32_16x16x32_bf16 v[2:5], v[166:169], v[198:201], v[2:5]
	v_mfma_f32_16x16x32_bf16 v[46:49], v[156:159], v[178:181], v[46:49]
	v_mfma_f32_16x16x32_bf16 v[42:45], v[170:173], v[178:181], v[42:45]
	v_mfma_f32_16x16x32_bf16 v[38:41], v[156:159], v[186:189], v[38:41]
	v_mfma_f32_16x16x32_bf16 v[34:37], v[170:173], v[186:189], v[34:37]
	v_mfma_f32_16x16x32_bf16 v[18:21], v[156:159], v[194:197], v[18:21]
	v_mfma_f32_16x16x32_bf16 v[14:17], v[170:173], v[194:197], v[14:17]
	v_mfma_f32_16x16x32_bf16 v[6:9], v[156:159], v[202:205], v[6:9]
	v_mfma_f32_16x16x32_bf16 v[2:5], v[170:173], v[202:205], v[2:5]
	s_barrier
	s_setprio 0
	s_add_i32 s29, s29, 2
	s_add_u32 s27, s27, 0x100
	s_addc_u32 s28, s28, 0
	s_cmpk_gt_u32 s29, 0x53
	s_mov_b64 s[54:55], s[4:5]
	s_cbranch_scc0 .LBB0_1476
	s_and_b64 vcc, exec, s[46:47]
	s_cbranch_vccz .LBB0_1479
	s_barrier

; #define PG8_STAGE(bufoff, gbase, voff) do { _Pragma("unroll") for (int _i = 0; _i < 2; ++_i) \
;         __builtin_amdgcn_global_load_lds((const unsigned*)((const char*)(gbase) + (voff)[_i]), (LAS unsigned*)(lds + (bufoff) + ldsw + _i * 8192), 16, 0, 0); } while (0)
; #define PG8_LDA(dst, b, h) do { _Pragma("unroll") for (int m = 0; m < 4; ++m) _Pragma("unroll") for (int k = 0; k < 2; ++k) dst[m][k] = *(const LAS bf16x8*)(lds + PG8_SA(b, h) + aoff + m * 2048 + k * 1024); } while (0)
; #define PG8_LDB(dst, b, h) do { _Pragma("unroll") for (int n = 0; n < 2; ++n) _Pragma("unroll") for (int k = 0; k < 2; ++k) dst[n][k] = *(const LAS bf16x8*)(lds + PG8_SB(b, h) + boff + n * 2048 + k * 1024); } while (0)
; #define PG8_MMA(ai, bj, At, Bt) do { __builtin_amdgcn_s_setprio(1); _Pragma("unroll") for (int m = 0; m < 4; ++m) _Pragma("unroll") for (int n = 0; n < 2; ++n) _Pragma("unroll") for (int k = 0; k < 2; ++k) \
;         acc[ai][bj][m][n] = __builtin_amdgcn_mfma_f32_16x16x32_bf16(Bt[n][k], At[m][k], acc[ai][bj][m][n], 0, 0, 0); __builtin_amdgcn_s_setprio(0); } while (0)
; #define PG8_WAIT_V(n) asm volatile("s_waitcnt vmcnt(" #n ")" ::: "memory")
; #define PG8_WAIT_L(n) asm volatile("s_waitcnt lgkmcnt(" #n ")" ::: "memory")
; #define PG8_BAR __builtin_amdgcn_s_barrier()
; #define PG8_SCHED __builtin_amdgcn_sched_barrier(0)
; template <class Epi, int AMODE>
; __device__ __forceinline__ void gemm_phase(LAS unsigned char* lds, const Gemm g, const StaticOrder& S, const Epi& E, int stagger_us, int tid_in) {
;     ...
;             const bool last = (t == nt - 2);
;             const char* a1 = cA + (size_t)(t + 1) * kstep;
;             const char* a2 = last ? nA : cA + (size_t)(t + 2) * kstep; const char* b2 = last ? nB : cB + (size_t)(t + 2) * kstep;
;             const char* a3 = a2 + kstep; const char* b3 = b2 + kstep;
;             PG8_LDB(B0, 0, 0); PG8_LDB(B1, 0, 1); PG8_SCHED; PG8_LDA(At, 0, 0); PG8_STAGE(PG8_SA(1, 1), a1 + hstepA, voffA);
;             PG8_WAIT_V(8); PG8_WAIT_L(0); PG8_BAR; PG8_MMA(0, 0, At, B0); PG8_MMA(0, 1, At, B1); PG8_BAR; PG8_SCHED;
;             PG8_LDA(At, 0, 1); PG8_STAGE(PG8_SB(0, 0), b2, voffB); PG8_STAGE(PG8_SB(0, 1), b2 + hstepB, voffB); PG8_STAGE(PG8_SA(0, 0), a2, voffA);
.LBB0_1498:
	s_add_u32 s4, s46, 0x100
	s_addc_u32 s5, s47, 0
	s_add_i32 s30, 0, 0x10000
	s_cmpk_eq_i32 s29, 0x52
	s_cselect_b32 s59, s41, s5
	s_cselect_b32 s58, s40, s4
	s_cselect_b32 s7, s57, s28
	s_cselect_b32 s6, s56, s27
	s_add_i32 s34, 0, 0x14000
	v_add_u32_e32 v62, s30, v209
	v_add_u32_e32 v158, s34, v209
	ds_read_b128 v[50:53], v62
	ds_read_b128 v[54:57], v62 offset:1024
	ds_read_b128 v[58:61], v62 offset:2048
	ds_read_b128 v[62:65], v62 offset:3072
	ds_read_b128 v[146:149], v158
	ds_read_b128 v[150:153], v158 offset:1024
	ds_read_b128 v[154:157], v158 offset:2048
	ds_read_b128 v[158:161], v158 offset:3072
	v_lshl_add_u64 v[200:201], s[46:47], 0, v[176:177]
	s_add_i32 m0, s13, 0xc000
	ds_read_b128 v[162:165], v215
	ds_read_b128 v[166:169], v215 offset:1024
	ds_read_b128 v[170:173], v215 offset:2048
	ds_read_b128 v[180:183], v215 offset:3072
	ds_read_b128 v[184:187], v215 offset:4096
	ds_read_b128 v[188:191], v215 offset:5120
	ds_read_b128 v[192:195], v215 offset:6144
	ds_read_b128 v[196:199], v215 offset:7168
	global_load_lds_dwordx4 v[200:201], off
	s_add_i32 m0, s13, 0xe000
	v_lshl_add_u64 v[200:201], s[46:47], 0, v[178:179]
	global_load_lds_dwordx4 v[200:201], off
	s_setprio 1
	s_waitcnt vmcnt(8) lgkmcnt(0)
	s_barrier
	v_mfma_f32_16x16x32_bf16 v[142:145], v[50:53], v[162:165], v[142:145]
	v_mfma_f32_16x16x32_bf16 v[138:141], v[58:61], v[162:165], v[138:141]
	v_mfma_f32_16x16x32_bf16 v[126:129], v[50:53], v[170:173], v[126:129]
	v_mfma_f32_16x16x32_bf16 v[122:125], v[58:61], v[170:173], v[122:125]
	v_mfma_f32_16x16x32_bf16 v[110:113], v[50:53], v[184:187], v[110:113]
	v_mfma_f32_16x16x32_bf16 v[106:109], v[58:61], v[184:187], v[106:109]
	v_mfma_f32_16x16x32_bf16 v[94:97], v[50:53], v[192:195], v[94:97]
	v_mfma_f32_16x16x32_bf16 v[90:93], v[58:61], v[192:195], v[90:93]
	v_mfma_f32_16x16x32_bf16 v[142:145], v[54:57], v[166:169], v[142:145]
	v_mfma_f32_16x16x32_bf16 v[138:141], v[62:65], v[166:169], v[138:141]
	v_mfma_f32_16x16x32_bf16 v[126:129], v[54:57], v[180:183], v[126:129]
	v_mfma_f32_16x16x32_bf16 v[122:125], v[62:65], v[180:183], v[122:125]
	v_mfma_f32_16x16x32_bf16 v[110:113], v[54:57], v[188:191], v[110:113]
	v_mfma_f32_16x16x32_bf16 v[106:109], v[62:65], v[188:191], v[106:109]
	v_mfma_f32_16x16x32_bf16 v[94:97], v[54:57], v[196:199], v[94:97]
	v_mfma_f32_16x16x32_bf16 v[90:93], v[62:65], v[196:199], v[90:93]
	v_mfma_f32_16x16x32_bf16 v[134:137], v[146:149], v[162:165], v[134:137]
	v_mfma_f32_16x16x32_bf16 v[130:133], v[154:157], v[162:165], v[130:133]
	v_mfma_f32_16x16x32_bf16 v[118:121], v[146:149], v[170:173], v[118:121]
	v_mfma_f32_16x16x32_bf16 v[114:117], v[154:157], v[170:173], v[114:117]
	v_mfma_f32_16x16x32_bf16 v[102:105], v[146:149], v[184:187], v[102:105]
	v_mfma_f32_16x16x32_bf16 v[98:101], v[154:157], v[184:187], v[98:101]
	v_mfma_f32_16x16x32_bf16 v[86:89], v[146:149], v[192:195], v[86:89]
	v_mfma_f32_16x16x32_bf16 v[82:85], v[154:157], v[192:195], v[82:85]
	v_mfma_f32_16x16x32_bf16 v[134:137], v[150:153], v[166:169], v[134:137]
	v_mfma_f32_16x16x32_bf16 v[130:133], v[158:161], v[166:169], v[130:133]
	v_mfma_f32_16x16x32_bf16 v[118:121], v[150:153], v[180:183], v[118:121]
	v_mfma_f32_16x16x32_bf16 v[114:117], v[158:161], v[180:183], v[114:117]
	v_mfma_f32_16x16x32_bf16 v[102:105], v[150:153], v[188:191], v[102:105]
	v_mfma_f32_16x16x32_bf16 v[98:101], v[158:161], v[188:191], v[98:101]
	v_mfma_f32_16x16x32_bf16 v[86:89], v[150:153], v[196:199], v[86:89]
	v_mfma_f32_16x16x32_bf16 v[82:85], v[158:161], v[196:199], v[82:85]
	s_barrier
	s_setprio 0
	s_add_i32 s30, s30, s12
	v_lshl_add_u64 v[200:201], s[6:7], 0, v[0:1]
	s_mov_b32 m0, s30
	ds_read_b128 v[162:165], v215 offset:16384
	ds_read_b128 v[166:169], v215 offset:17408
	ds_read_b128 v[170:173], v215 offset:18432
	ds_read_b128 v[180:183], v215 offset:19456
	ds_read_b128 v[184:187], v215 offset:20480
	ds_read_b128 v[188:191], v215 offset:21504
	ds_read_b128 v[192:195], v215 offset:22528
	ds_read_b128 v[196:199], v215 offset:23552
	global_load_lds_dwordx4 v[200:201], off
	s_add_i32 m0, s30, 0x2000
	s_add_u32 s30, s6, 0x158000
	v_lshl_add_u64 v[202:203], s[6:7], 0, v[174:175]
	s_addc_u32 s31, s7, 0
	s_add_i32 s34, s34, s12
	global_load_lds_dwordx4 v[202:203], off
	v_lshl_add_u64 v[204:205], s[30:31], 0, v[0:1]
	s_mov_b32 m0, s34
	v_lshl_add_u64 v[206:207], s[58:59], 0, v[174:175]
	global_load_lds_dwordx4 v[204:205], off
	s_add_i32 m0, s34, 0x2000
	v_lshl_add_u64 v[204:205], s[30:31], 0, v[174:175]
	global_load_lds_dwordx4 v[204:205], off
	s_mov_b32 m0, s13
	v_lshl_add_u64 v[204:205], s[58:59], 0, v[0:1]
	global_load_lds_dwordx4 v[204:205], off
	s_mov_b32 m0, s24
	s_nop 0
	global_load_lds_dwordx4 v[206:207], off
	s_setprio 1
	s_waitcnt vmcnt(8) lgkmcnt(0)
	s_barrier
; #define PG8_STAGE(bufoff, gbase, voff) do { _Pragma("unroll") for (int _i = 0; _i < 2; ++_i) \
;         __builtin_amdgcn_global_load_lds((const unsigned*)((const char*)(gbase) + (voff)[_i]), (LAS unsigned*)(lds + (bufoff) + ldsw + _i * 8192), 16, 0, 0); } while (0)
; #define PG8_LDA(dst, b, h) do { _Pragma("unroll") for (int m = 0; m < 4; ++m) _Pragma("unroll") for (int k = 0; k < 2; ++k) dst[m][k] = *(const LAS bf16x8*)(lds + PG8_SA(b, h) + aoff + m * 2048 + k * 1024); } while (0)
; #define PG8_LDB(dst, b, h) do { _Pragma("unroll") for (int n = 0; n < 2; ++n) _Pragma("unroll") for (int k = 0; k < 2; ++k) dst[n][k] = *(const LAS bf16x8*)(lds + PG8_SB(b, h) + boff + n * 2048 + k * 1024); } while (0)
; #define PG8_MMA(ai, bj, At, Bt) do { __builtin_amdgcn_s_setprio(1); _Pragma("unroll") for (int m = 0; m < 4; ++m) _Pragma("unroll") for (int n = 0; n < 2; ++n) _Pragma("unroll") for (int k = 0; k < 2; ++k) \
;         acc[ai][bj][m][n] = __builtin_amdgcn_mfma_f32_16x16x32_bf16(Bt[n][k], At[m][k], acc[ai][bj][m][n], 0, 0, 0); __builtin_amdgcn_s_setprio(0); } while (0)
; #define PG8_WAIT_V(n) asm volatile("s_waitcnt vmcnt(" #n ")" ::: "memory")
; #define PG8_WAIT_L(n) asm volatile("s_waitcnt lgkmcnt(" #n ")" ::: "memory")
; #define PG8_BAR __builtin_amdgcn_s_barrier()
; #define PG8_SCHED __builtin_amdgcn_sched_barrier(0)
; template <class Epi, int AMODE>
; __device__ __forceinline__ void gemm_phase(LAS unsigned char* lds, const Gemm g, const StaticOrder& S, const Epi& E, int stagger_us, int tid_in) {
;     ...
;             PG8_WAIT_V(8); PG8_WAIT_L(0); PG8_BAR; PG8_MMA(1, 0, At, B0); PG8_MMA(1, 1, At, B1); PG8_BAR; PG8_SCHED;
;             PG8_LDB(B0, 1, 0); PG8_LDB(B1, 1, 1); PG8_SCHED; PG8_LDA(At, 1, 0); PG8_STAGE(PG8_SA(0, 1), a2 + hstepA, voffA);
;             PG8_WAIT_V(8); PG8_WAIT_L(0); PG8_BAR; PG8_MMA(0, 0, At, B0); PG8_MMA(0, 1, At, B1); PG8_BAR; PG8_SCHED;
	v_mfma_f32_16x16x32_bf16 v[78:81], v[50:53], v[162:165], v[78:81]
	v_mfma_f32_16x16x32_bf16 v[74:77], v[58:61], v[162:165], v[74:77]
	v_mfma_f32_16x16x32_bf16 v[46:49], v[50:53], v[170:173], v[46:49]
	v_mfma_f32_16x16x32_bf16 v[42:45], v[58:61], v[170:173], v[42:45]
	v_mfma_f32_16x16x32_bf16 v[30:33], v[50:53], v[184:187], v[30:33]
	v_mfma_f32_16x16x32_bf16 v[26:29], v[58:61], v[184:187], v[26:29]
	v_mfma_f32_16x16x32_bf16 v[14:17], v[50:53], v[192:195], v[14:17]
	v_mfma_f32_16x16x32_bf16 v[10:13], v[58:61], v[192:195], v[10:13]
	v_mfma_f32_16x16x32_bf16 v[78:81], v[54:57], v[166:169], v[78:81]
	v_mfma_f32_16x16x32_bf16 v[74:77], v[62:65], v[166:169], v[74:77]
	v_mfma_f32_16x16x32_bf16 v[46:49], v[54:57], v[180:183], v[46:49]
	v_mfma_f32_16x16x32_bf16 v[42:45], v[62:65], v[180:183], v[42:45]
	v_mfma_f32_16x16x32_bf16 v[30:33], v[54:57], v[188:191], v[30:33]
	v_mfma_f32_16x16x32_bf16 v[26:29], v[62:65], v[188:191], v[26:29]
	v_mfma_f32_16x16x32_bf16 v[14:17], v[54:57], v[196:199], v[14:17]
	v_mfma_f32_16x16x32_bf16 v[10:13], v[62:65], v[196:199], v[10:13]
	v_mfma_f32_16x16x32_bf16 v[38:41], v[146:149], v[170:173], v[38:41]
	v_mfma_f32_16x16x32_bf16 v[34:37], v[154:157], v[170:173], v[34:37]
	v_mfma_f32_16x16x32_bf16 v[22:25], v[146:149], v[184:187], v[22:25]
	v_mfma_f32_16x16x32_bf16 v[18:21], v[154:157], v[184:187], v[18:21]
	v_mfma_f32_16x16x32_bf16 v[6:9], v[146:149], v[192:195], v[6:9]
	v_mfma_f32_16x16x32_bf16 v[2:5], v[154:157], v[192:195], v[2:5]
	v_mfma_f32_16x16x32_bf16 v[50:53], v[146:149], v[162:165], v[70:73]
	v_mfma_f32_16x16x32_bf16 v[54:57], v[154:157], v[162:165], v[66:69]
	v_mfma_f32_16x16x32_bf16 v[38:41], v[150:153], v[180:183], v[38:41]
	v_mfma_f32_16x16x32_bf16 v[34:37], v[158:161], v[180:183], v[34:37]
	v_mfma_f32_16x16x32_bf16 v[22:25], v[150:153], v[188:191], v[22:25]
	v_mfma_f32_16x16x32_bf16 v[18:21], v[158:161], v[188:191], v[18:21]
	v_mfma_f32_16x16x32_bf16 v[6:9], v[150:153], v[196:199], v[6:9]
	v_mfma_f32_16x16x32_bf16 v[2:5], v[158:161], v[196:199], v[2:5]
	v_mfma_f32_16x16x32_bf16 v[50:53], v[150:153], v[166:169], v[50:53]
	v_mfma_f32_16x16x32_bf16 v[54:57], v[158:161], v[166:169], v[54:57]
	s_barrier
	s_setprio 0
	s_add_i32 s34, 0, 0x18000
	s_add_i32 s35, 0, 0x1c000
	v_add_u32_e32 v70, s34, v209
	v_add_u32_e32 v158, s35, v209
	ds_read_b128 v[58:61], v70
	ds_read_b128 v[62:65], v70 offset:1024
	ds_read_b128 v[66:69], v70 offset:2048
	ds_read_b128 v[70:73], v70 offset:3072
	ds_read_b128 v[146:149], v158
	ds_read_b128 v[150:153], v158 offset:1024
	ds_read_b128 v[154:157], v158 offset:2048
	ds_read_b128 v[158:161], v158 offset:3072
	s_add_u32 s30, s58, 0x158000
	s_addc_u32 s31, s59, 0
	s_mov_b32 m0, s25
	v_lshl_add_u64 v[210:211], s[30:31], 0, v[0:1]
	ds_read_b128 v[162:165], v215 offset:32768
	ds_read_b128 v[166:169], v215 offset:33792
	ds_read_b128 v[170:173], v215 offset:34816
	ds_read_b128 v[180:183], v215 offset:35840
	ds_read_b128 v[184:187], v215 offset:36864
	ds_read_b128 v[188:191], v215 offset:37888
	ds_read_b128 v[192:195], v215 offset:38912
	ds_read_b128 v[196:199], v215 offset:39936
	global_load_lds_dwordx4 v[210:211], off
	s_mov_b32 m0, s66
	v_lshl_add_u64 v[210:211], s[30:31], 0, v[174:175]
	global_load_lds_dwordx4 v[210:211], off
	s_setprio 1
	s_waitcnt vmcnt(8) lgkmcnt(0)
	s_barrier
	v_mfma_f32_16x16x32_bf16 v[142:145], v[58:61], v[162:165], v[142:145]
	v_mfma_f32_16x16x32_bf16 v[138:141], v[66:69], v[162:165], v[138:141]
	v_mfma_f32_16x16x32_bf16 v[126:129], v[58:61], v[170:173], v[126:129]
	v_mfma_f32_16x16x32_bf16 v[122:125], v[66:69], v[170:173], v[122:125]
	v_mfma_f32_16x16x32_bf16 v[110:113], v[58:61], v[184:187], v[110:113]
	v_mfma_f32_16x16x32_bf16 v[106:109], v[66:69], v[184:187], v[106:109]
	v_mfma_f32_16x16x32_bf16 v[94:97], v[58:61], v[192:195], v[94:97]
	v_mfma_f32_16x16x32_bf16 v[90:93], v[66:69], v[192:195], v[90:93]
	v_mfma_f32_16x16x32_bf16 v[142:145], v[62:65], v[166:169], v[142:145]
	v_mfma_f32_16x16x32_bf16 v[138:141], v[70:73], v[166:169], v[138:141]
	v_mfma_f32_16x16x32_bf16 v[126:129], v[62:65], v[180:183], v[126:129]
	v_mfma_f32_16x16x32_bf16 v[122:125], v[70:73], v[180:183], v[122:125]
	v_mfma_f32_16x16x32_bf16 v[110:113], v[62:65], v[188:191], v[110:113]
	v_mfma_f32_16x16x32_bf16 v[106:109], v[70:73], v[188:191], v[106:109]
	v_mfma_f32_16x16x32_bf16 v[94:97], v[62:65], v[196:199], v[94:97]
	v_mfma_f32_16x16x32_bf16 v[90:93], v[70:73], v[196:199], v[90:93]
	v_mfma_f32_16x16x32_bf16 v[134:137], v[146:149], v[162:165], v[134:137]
	v_mfma_f32_16x16x32_bf16 v[130:133], v[154:157], v[162:165], v[130:133]
	v_mfma_f32_16x16x32_bf16 v[118:121], v[146:149], v[170:173], v[118:121]
	v_mfma_f32_16x16x32_bf16 v[114:117], v[154:157], v[170:173], v[114:117]
	v_mfma_f32_16x16x32_bf16 v[102:105], v[146:149], v[184:187], v[102:105]
	v_mfma_f32_16x16x32_bf16 v[98:101], v[154:157], v[184:187], v[98:101]
	v_mfma_f32_16x16x32_bf16 v[86:89], v[146:149], v[192:195], v[86:89]
	v_mfma_f32_16x16x32_bf16 v[82:85], v[154:157], v[192:195], v[82:85]
	v_mfma_f32_16x16x32_bf16 v[134:137], v[150:153], v[166:169], v[134:137]
	v_mfma_f32_16x16x32_bf16 v[130:133], v[158:161], v[166:169], v[130:133]
	v_mfma_f32_16x16x32_bf16 v[118:121], v[150:153], v[180:183], v[118:121]
	v_mfma_f32_16x16x32_bf16 v[114:117], v[158:161], v[180:183], v[114:117]
	v_mfma_f32_16x16x32_bf16 v[102:105], v[150:153], v[188:191], v[102:105]
	v_mfma_f32_16x16x32_bf16 v[98:101], v[158:161], v[188:191], v[98:101]
	v_mfma_f32_16x16x32_bf16 v[86:89], v[150:153], v[196:199], v[86:89]
	v_mfma_f32_16x16x32_bf16 v[82:85], v[158:161], v[196:199], v[82:85]
	s_barrier
; #define PG8_STAGE(bufoff, gbase, voff) do { _Pragma("unroll") for (int _i = 0; _i < 2; ++_i) \
;         __builtin_amdgcn_global_load_lds((const unsigned*)((const char*)(gbase) + (voff)[_i]), (LAS unsigned*)(lds + (bufoff) + ldsw + _i * 8192), 16, 0, 0); } while (0)
; #define PG8_LDA(dst, b, h) do { _Pragma("unroll") for (int m = 0; m < 4; ++m) _Pragma("unroll") for (int k = 0; k < 2; ++k) dst[m][k] = *(const LAS bf16x8*)(lds + PG8_SA(b, h) + aoff + m * 2048 + k * 1024); } while (0)
; #define PG8_MMA(ai, bj, At, Bt) do { __builtin_amdgcn_s_setprio(1); _Pragma("unroll") for (int m = 0; m < 4; ++m) _Pragma("unroll") for (int n = 0; n < 2; ++n) _Pragma("unroll") for (int k = 0; k < 2; ++k) \
;         acc[ai][bj][m][n] = __builtin_amdgcn_mfma_f32_16x16x32_bf16(Bt[n][k], At[m][k], acc[ai][bj][m][n], 0, 0, 0); __builtin_amdgcn_s_setprio(0); } while (0)
; #define PG8_WAIT_V(n) asm volatile("s_waitcnt vmcnt(" #n ")" ::: "memory")
; #define PG8_WAIT_L(n) asm volatile("s_waitcnt lgkmcnt(" #n ")" ::: "memory")
; #define PG8_BAR __builtin_amdgcn_s_barrier()
; #define PG8_SCHED __builtin_amdgcn_sched_barrier(0)
; template <class Epi, int AMODE>
; __device__ __forceinline__ void gemm_phase(LAS unsigned char* lds, const Gemm g, const StaticOrder& S, const Epi& E, int stagger_us, int tid_in) {
;     ...
;             PG8_LDA(At, 1, 1); PG8_STAGE(PG8_SB(1, 0), b3, voffB); PG8_STAGE(PG8_SB(1, 1), b3 + hstepB, voffB); PG8_STAGE(PG8_SA(1, 0), a3, voffA);
;             PG8_WAIT_V(8); PG8_WAIT_L(0); PG8_BAR; PG8_MMA(1, 0, At, B0); PG8_MMA(1, 1, At, B1); PG8_BAR; PG8_SCHED;
;         }
;         if (wr == 0) PG8_BAR;
	s_setprio 0
	s_add_i32 s30, s34, s12
	v_lshl_add_u64 v[200:201], v[200:201], 0, s[74:75]
	s_mov_b32 m0, s30
	ds_read_b128 v[162:165], v215 offset:49152
	ds_read_b128 v[166:169], v215 offset:50176
	ds_read_b128 v[170:173], v215 offset:51200
	ds_read_b128 v[180:183], v215 offset:52224
	ds_read_b128 v[184:187], v215 offset:53248
	ds_read_b128 v[188:191], v215 offset:54272
	ds_read_b128 v[192:195], v215 offset:55296
	ds_read_b128 v[196:199], v215 offset:56320
	global_load_lds_dwordx4 v[200:201], off
	s_add_i32 m0, s30, 0x2000
	s_add_u32 s6, s6, 0x158080
	v_lshl_add_u64 v[200:201], v[202:203], 0, s[74:75]
	s_addc_u32 s7, s7, 0
	s_add_i32 s30, s35, s12
	global_load_lds_dwordx4 v[200:201], off
	s_mov_b32 m0, s30
	v_lshl_add_u64 v[200:201], s[6:7], 0, v[0:1]
	global_load_lds_dwordx4 v[200:201], off
	s_add_i32 m0, s30, 0x2000
	v_lshl_add_u64 v[200:201], s[6:7], 0, v[174:175]
	global_load_lds_dwordx4 v[200:201], off
	s_mov_b32 m0, s79
	v_lshl_add_u64 v[200:201], v[204:205], 0, s[74:75]
	global_load_lds_dwordx4 v[200:201], off
	s_mov_b32 m0, s83
	v_lshl_add_u64 v[200:201], v[206:207], 0, s[74:75]
	global_load_lds_dwordx4 v[200:201], off
	s_setprio 1
	s_waitcnt vmcnt(8) lgkmcnt(0)
	s_barrier
	v_mfma_f32_16x16x32_bf16 v[78:81], v[58:61], v[162:165], v[78:81]
	v_mfma_f32_16x16x32_bf16 v[74:77], v[66:69], v[162:165], v[74:77]
	v_mfma_f32_16x16x32_bf16 v[46:49], v[58:61], v[170:173], v[46:49]
	v_mfma_f32_16x16x32_bf16 v[42:45], v[66:69], v[170:173], v[42:45]
	v_mfma_f32_16x16x32_bf16 v[30:33], v[58:61], v[184:187], v[30:33]
	v_mfma_f32_16x16x32_bf16 v[26:29], v[66:69], v[184:187], v[26:29]
	v_mfma_f32_16x16x32_bf16 v[14:17], v[58:61], v[192:195], v[14:17]
	v_mfma_f32_16x16x32_bf16 v[10:13], v[66:69], v[192:195], v[10:13]
	v_mfma_f32_16x16x32_bf16 v[78:81], v[62:65], v[166:169], v[78:81]
	v_mfma_f32_16x16x32_bf16 v[74:77], v[70:73], v[166:169], v[74:77]
	v_mfma_f32_16x16x32_bf16 v[46:49], v[62:65], v[180:183], v[46:49]
	v_mfma_f32_16x16x32_bf16 v[42:45], v[70:73], v[180:183], v[42:45]
	v_mfma_f32_16x16x32_bf16 v[30:33], v[62:65], v[188:191], v[30:33]
	v_mfma_f32_16x16x32_bf16 v[26:29], v[70:73], v[188:191], v[26:29]
	v_mfma_f32_16x16x32_bf16 v[14:17], v[62:65], v[196:199], v[14:17]
	v_mfma_f32_16x16x32_bf16 v[10:13], v[70:73], v[196:199], v[10:13]
	v_mfma_f32_16x16x32_bf16 v[50:53], v[146:149], v[162:165], v[50:53]
	v_mfma_f32_16x16x32_bf16 v[70:73], v[150:153], v[166:169], v[50:53]
	v_mfma_f32_16x16x32_bf16 v[50:53], v[154:157], v[162:165], v[54:57]
	v_mfma_f32_16x16x32_bf16 v[38:41], v[146:149], v[170:173], v[38:41]
	v_mfma_f32_16x16x32_bf16 v[34:37], v[154:157], v[170:173], v[34:37]
	v_mfma_f32_16x16x32_bf16 v[22:25], v[146:149], v[184:187], v[22:25]
	v_mfma_f32_16x16x32_bf16 v[18:21], v[154:157], v[184:187], v[18:21]
	v_mfma_f32_16x16x32_bf16 v[6:9], v[146:149], v[192:195], v[6:9]
	v_mfma_f32_16x16x32_bf16 v[2:5], v[154:157], v[192:195], v[2:5]
	v_mfma_f32_16x16x32_bf16 v[66:69], v[158:161], v[166:169], v[50:53]
	v_mfma_f32_16x16x32_bf16 v[38:41], v[150:153], v[180:183], v[38:41]
	v_mfma_f32_16x16x32_bf16 v[34:37], v[158:161], v[180:183], v[34:37]
	v_mfma_f32_16x16x32_bf16 v[22:25], v[150:153], v[188:191], v[22:25]
	v_mfma_f32_16x16x32_bf16 v[18:21], v[158:161], v[188:191], v[18:21]
	v_mfma_f32_16x16x32_bf16 v[6:9], v[150:153], v[196:199], v[6:9]
	v_mfma_f32_16x16x32_bf16 v[2:5], v[158:161], v[196:199], v[2:5]
	s_barrier
	s_setprio 0
	s_add_i32 s29, s29, 2
	s_add_u32 s27, s27, 0x100
	s_addc_u32 s28, s28, 0
	s_cmpk_gt_u32 s29, 0x53
	s_mov_b64 s[46:47], s[4:5]
	s_cbranch_scc0 .LBB0_1498
	s_and_b64 vcc, exec, s[54:55]
	s_cbranch_vccz .LBB0_1501
	s_barrier
